# norm/GEMM/final phases read with L1-bypassing sc1 loads so the XCD-local barriers between them also skip the L1 invalidate (local mode only; fallback keeps it)
# speedup vs baseline: 1.0196x; 1.0077x over previous
.LBB0_192:
	v_mov_b32_e32 v2, v228
	s_add_i32 s3, s3, s20
	v_ashrrev_i32_e32 v0, 6, v2
	v_add_u32_e32 v8, s2, v0
	v_add_u32_e32 v0, 0xffffe000, v8
	v_ashrrev_i32_e32 v0, 12, v0
	v_mad_i32_i24 v0, v0, s28, s28
	v_cmp_lt_i32_e32 vcc, s22, v8
	v_ashrrev_i32_e32 v9, 31, v8
	v_lshlrev_b32_e32 v2, 2, v2
	v_cndmask_b32_e32 v10, 0, v0, vcc
	v_lshlrev_b64 v[0:1], 12, v[8:9]
	v_and_b32_e32 v44, 0xfc, v2
	v_lshl_add_u64 v[0:1], s[88:89], 0, v[0:1]
	v_lshlrev_b32_e32 v196, 2, v44
	v_lshl_add_u64 v[14:15], v[0:1], 0, v[196:197]
	global_load_dwordx4 v[4:7], v[14:15], off offset:2048 sc1
	global_load_dwordx4 v[0:3], v[14:15], off offset:3072 sc1
	v_ashrrev_i32_e32 v11, 31, v10
	v_lshl_add_u64 v[10:11], v[10:11], 2, s[72:73]
	v_lshlrev_b64 v[8:9], 11, v[8:9]
	v_lshl_add_u64 v[18:19], s[40:41], 0, v[8:9]
	s_add_i32 s2, s2, s35
	s_cmpk_gt_i32 s3, 0x1ff
	s_waitcnt vmcnt(1)
	v_mov_b32_e32 v16, v5
	s_waitcnt vmcnt(0)
	v_mov_b32_e32 v17, v1
	v_mov_b32_e32 v12, v4
	v_mov_b32_e32 v13, v0
	v_pk_mul_f32 v[16:17], v[16:17], v[16:17]
	s_nop 0
	v_pk_fma_f32 v[12:13], v[12:13], v[12:13], v[16:17]
	v_mov_b32_e32 v16, v6
	v_mov_b32_e32 v17, v2
	v_pk_fma_f32 v[12:13], v[16:17], v[16:17], v[12:13]
	v_mov_b32_e32 v16, v7
	v_mov_b32_e32 v17, v3
	v_pk_fma_f32 v[36:37], v[16:17], v[16:17], v[12:13]
	v_lshl_add_u64 v[16:17], v[10:11], 0, s[36:37]
	v_lshl_add_u64 v[8:9], v[16:17], 0, v[196:197]
	v_lshl_add_u64 v[12:13], v[10:11], 0, v[196:197]
	global_load_dwordx4 v[20:23], v[14:15], off sc1
	global_load_dwordx4 v[24:27], v196, s[0:1] sc1
	global_load_dwordx4 v[28:31], v[8:9], off sc1
	global_load_dwordx4 v[32:35], v[12:13], off sc1
	s_waitcnt vmcnt(3)
	v_mov_b32_e32 v42, v21
	global_load_dwordx4 v[8:11], v[14:15], off offset:1024 sc1
	v_mov_b32_e32 v40, v20
	v_mov_b32_e32 v14, v22
	v_mov_b32_e32 v38, v23
	s_waitcnt vmcnt(2)
	v_pk_add_f32 v[28:29], v[28:29], 1.0 op_sel_hi:[1,0]
	s_waitcnt vmcnt(0)
	v_mov_b32_e32 v43, v9
	v_mov_b32_e32 v41, v8
	v_pk_mul_f32 v[42:43], v[42:43], v[42:43]
	v_mov_b32_e32 v15, v10
	v_pk_fma_f32 v[40:41], v[40:41], v[40:41], v[42:43]
	v_mov_b32_e32 v39, v11
	v_pk_fma_f32 v[14:15], v[14:15], v[14:15], v[40:41]
	s_nop 0
	v_pk_fma_f32 v[14:15], v[38:39], v[38:39], v[14:15]
	s_nop 0
	v_add_f32_e32 v14, v14, v15
	v_add_f32_e32 v14, v14, v36
	v_add_f32_e32 v14, v14, v37
	s_nop 1
	v_add_f32_dpp v14, v14, v14 quad_perm:[1,0,3,2] row_mask:0xf bank_mask:0xf bound_ctrl:1
	s_nop 1
	v_add_f32_dpp v14, v14, v14 quad_perm:[2,3,0,1] row_mask:0xf bank_mask:0xf bound_ctrl:1
	s_nop 1
	v_add_f32_dpp v14, v14, v14 row_ror:4 row_mask:0xf bank_mask:0xf bound_ctrl:1
	s_nop 1
	v_add_f32_dpp v14, v14, v14 row_ror:8 row_mask:0xf bank_mask:0xf bound_ctrl:1
	s_nop 0
	v_readlane_b32 s6, v14, 16
	v_readlane_b32 s7, v14, 48
	v_readlane_b32 s4, v14, 0
	v_readlane_b32 s5, v14, 32
	v_mov_b32_e32 v14, s6
	v_mov_b32_e32 v15, s7
	v_pk_add_f32 v[14:15], s[4:5], v[14:15]
	s_nop 0
	v_add_f32_e32 v14, v14, v15
	v_fmamk_f32 v14, v14, 0x3a800000, v229
	v_cmp_gt_f32_e32 vcc, s69, v14
	v_mul_f32_e32 v15, 0x4b800000, v14
	s_nop 0
	v_cndmask_b32_e32 v14, v14, v15, vcc
	v_rsq_f32_e32 v14, v14
	s_nop 0
	v_mul_f32_e32 v15, 0x45800000, v14
	v_cndmask_b32_e32 v14, v14, v15, vcc
	v_pk_mul_f32 v[20:21], v[20:21], v[14:15] op_sel_hi:[1,0]
	v_pk_mul_f32 v[22:23], v[22:23], v[14:15] op_sel_hi:[1,0]
	v_pk_mul_f32 v[20:21], v[24:25], v[20:21]
	v_pk_mul_f32 v[22:23], v[26:27], v[22:23]
	v_pk_add_f32 v[24:25], v[30:31], 1.0 op_sel_hi:[1,0]
	v_pk_fma_f32 v[20:21], v[28:29], v[20:21], v[32:33]
	v_pk_fma_f32 v[22:23], v[24:25], v[22:23], v[34:35]
	v_cvt_pk_bf16_f32 v20, v20, v21
	v_cvt_pk_bf16_f32 v21, v22, v23
	v_lshlrev_b32_e32 v22, 1, v44
	v_mov_b32_e32 v23, v197
	v_lshl_add_u64 v[18:19], v[18:19], 0, v[22:23]
	global_store_dwordx2 v[18:19], v[20:21], off
	v_or_b32_e32 v20, 0x400, v196
	v_mov_b32_e32 v21, v197
	v_lshl_add_u64 v[24:25], v[16:17], 0, v[20:21]
	global_load_dwordx4 v[20:23], v196, s[0:1] offset:1024 sc1
	s_nop 0
	global_load_dwordx4 v[24:27], v[24:25], off sc1
	s_nop 0
	global_load_dwordx4 v[28:31], v[12:13], off offset:1024 sc1
	v_pk_mul_f32 v[8:9], v[8:9], v[14:15] op_sel_hi:[1,0]
	v_pk_mul_f32 v[10:11], v[10:11], v[14:15] op_sel_hi:[1,0]
	v_pk_mul_f32 v[4:5], v[4:5], v[14:15] op_sel_hi:[1,0]
	v_pk_mul_f32 v[6:7], v[6:7], v[14:15] op_sel_hi:[1,0]
	v_pk_mul_f32 v[0:1], v[0:1], v[14:15] op_sel_hi:[1,0]
	v_pk_mul_f32 v[2:3], v[2:3], v[14:15] op_sel_hi:[1,0]
	s_waitcnt vmcnt(2)
	v_pk_mul_f32 v[8:9], v[8:9], v[20:21]
	s_waitcnt vmcnt(1)
	v_pk_add_f32 v[20:21], v[24:25], 1.0 op_sel_hi:[1,0]
	v_pk_mul_f32 v[10:11], v[10:11], v[22:23]
	s_waitcnt vmcnt(0)
	v_pk_fma_f32 v[8:9], v[8:9], v[20:21], v[28:29]
	v_pk_add_f32 v[20:21], v[26:27], 1.0 op_sel_hi:[1,0]
	v_cvt_pk_bf16_f32 v8, v8, v9
	v_pk_fma_f32 v[10:11], v[10:11], v[20:21], v[30:31]
	s_nop 0
	v_cvt_pk_bf16_f32 v9, v10, v11
	global_store_dwordx2 v[18:19], v[8:9], off offset:512
	v_or_b32_e32 v8, 0x800, v196
	v_mov_b32_e32 v9, v197
	v_lshl_add_u64 v[20:21], v[16:17], 0, v[8:9]
	global_load_dwordx4 v[8:11], v196, s[0:1] offset:2048 sc1
	s_nop 0
	global_load_dwordx4 v[20:23], v[20:21], off sc1
	s_nop 0
	global_load_dwordx4 v[24:27], v[12:13], off offset:2048 sc1
	s_waitcnt vmcnt(2)
	v_pk_mul_f32 v[4:5], v[4:5], v[8:9]
	s_waitcnt vmcnt(1)
	v_pk_add_f32 v[8:9], v[20:21], 1.0 op_sel_hi:[1,0]
	v_pk_mul_f32 v[6:7], v[6:7], v[10:11]
	s_waitcnt vmcnt(0)
	v_pk_fma_f32 v[4:5], v[4:5], v[8:9], v[24:25]
	v_pk_add_f32 v[8:9], v[22:23], 1.0 op_sel_hi:[1,0]
	v_cvt_pk_bf16_f32 v4, v4, v5
	v_pk_fma_f32 v[6:7], v[6:7], v[8:9], v[26:27]
	s_nop 0
	v_cvt_pk_bf16_f32 v5, v6, v7
	global_store_dwordx2 v[18:19], v[4:5], off offset:1024
	v_or_b32_e32 v4, 0xc00, v196
	v_mov_b32_e32 v5, v197
	v_lshl_add_u64 v[8:9], v[16:17], 0, v[4:5]
	global_load_dwordx4 v[4:7], v196, s[0:1] offset:3072 sc1
	s_nop 0
	global_load_dwordx4 v[8:11], v[8:9], off sc1
	s_nop 0
	global_load_dwordx4 v[20:23], v[12:13], off offset:3072 sc1
	s_waitcnt vmcnt(2)
	v_pk_mul_f32 v[0:1], v[0:1], v[4:5]
	s_waitcnt vmcnt(1)
	v_pk_add_f32 v[4:5], v[8:9], 1.0 op_sel_hi:[1,0]
	v_pk_mul_f32 v[2:3], v[2:3], v[6:7]
	s_waitcnt vmcnt(0)
	v_pk_fma_f32 v[0:1], v[0:1], v[4:5], v[20:21]
	v_pk_add_f32 v[4:5], v[10:11], 1.0 op_sel_hi:[1,0]
	v_cvt_pk_bf16_f32 v0, v0, v1
	v_pk_fma_f32 v[2:3], v[2:3], v[4:5], v[22:23]
	s_nop 0
	v_cvt_pk_bf16_f32 v1, v2, v3
	global_store_dwordx2 v[18:19], v[0:1], off offset:1536
	s_cbranch_scc0 .LBB0_192

.LBB0_224:
	s_or_b64 exec, exec, s[8:9]
	s_waitcnt vmcnt(0)
	v_readlane_b32 s2, v255, 12
	s_cmp_lg_u32 s2, 0
	s_cbranch_scc1 .Lxb_noinv_0_1
	buffer_inv sc1
.Lxb_noinv_0_1:
	s_waitcnt vmcnt(0)

.Lxb_local_0:
	s_mov_b64 s[6:7], exec
	v_mbcnt_lo_u32_b32 v0, s6, 0
	v_mbcnt_hi_u32_b32 v0, s7, v0
	v_cmp_eq_u32_e32 vcc, 0, v0
	s_waitcnt vmcnt(0)
	v_readlane_b32 s2, v255, 12
	s_cmp_lg_u32 s2, 0
	s_cbranch_scc1 .Lxb_noinv_0_0
	buffer_inv sc1
.Lxb_noinv_0_0:
	s_and_saveexec_b64 s[8:9], vcc
	s_cbranch_execz .LBB0_244
	s_bcnt1_i32_b64 s2, s[6:7]
	v_mov_b32_e32 v0, s2
	global_atomic_add v236, v0, s[4:5] offset:1024

.LBB0_249:
	s_and_b32 s2, s16, 15
	s_lshl_b32 s2, s2, 7
	v_add_u32_e32 v0, s2, v142
	v_ashrrev_i32_e32 v1, 31, v0
	v_lshlrev_b64 v[0:1], 11, v[0:1]
	v_lshl_add_u64 v[116:117], v[110:111], 0, v[0:1]
	v_add_u32_e32 v0, s2, v143
	v_ashrrev_i32_e32 v1, 31, v0
	v_lshlrev_b64 v[0:1], 11, v[0:1]
	v_lshl_add_u64 v[118:119], v[110:111], 0, v[0:1]
	v_add_u32_e32 v0, s2, v144
	v_ashrrev_i32_e32 v1, 31, v0
	v_lshlrev_b64 v[0:1], 11, v[0:1]
	v_lshl_add_u64 v[120:121], v[110:111], 0, v[0:1]
	v_add_u32_e32 v0, s2, v145
	v_ashrrev_i32_e32 v1, 31, v0
	s_lshl_b32 s2, s15, 11
	v_lshlrev_b64 v[0:1], 11, v[0:1]
	s_and_b32 s50, s2, 0x7c0000
	s_and_b32 s2, s15, 0xf80
	v_lshl_add_u64 v[122:123], v[110:111], 0, v[0:1]
	v_add_u32_e32 v0, s2, v97
	v_ashrrev_i32_e32 v1, 31, v0
	v_lshlrev_b64 v[0:1], 11, v[0:1]
	v_lshl_add_u64 v[126:127], v[114:115], 0, v[0:1]
	v_add_u32_e32 v0, s2, v146
	v_ashrrev_i32_e32 v1, 31, v0
	v_lshlrev_b64 v[0:1], 11, v[0:1]
	v_lshl_add_u64 v[128:129], v[114:115], 0, v[0:1]
	v_add_u32_e32 v0, s2, v147
	s_and_b32 s2, s17, 15
	v_readlane_b32 s3, v253, 46
	v_ashrrev_i32_e32 v1, 31, v0
	s_or_b32 s2, s2, s3
	v_lshlrev_b64 v[0:1], 11, v[0:1]
	s_lshl_b32 s3, s2, 7
	v_lshl_add_u64 v[130:131], v[114:115], 0, v[0:1]
	v_add_u32_e32 v0, s3, v96
	v_ashrrev_i32_e32 v1, 31, v0
	v_lshlrev_b64 v[0:1], 11, v[0:1]
	v_lshl_add_u64 v[12:13], v[98:99], 0, v[0:1]
	s_mov_b32 s2, 0x10000
	v_add_co_u32_e32 v4, vcc, s2, v12
	s_lshl_b32 s6, s17, 3
	s_nop 0
	v_addc_co_u32_e32 v5, vcc, 0, v13, vcc
	s_mov_b32 s2, 0x20000
	v_add_co_u32_e32 v8, vcc, s2, v12
	s_and_b32 s2, s6, 0xf80
	v_add_u32_e32 v16, s2, v96
	v_ashrrev_i32_e32 v17, 31, v16
	v_lshlrev_b64 v[16:17], 11, v[16:17]
	v_addc_co_u32_e32 v9, vcc, 0, v13, vcc
	v_lshl_add_u64 v[28:29], v[100:101], 0, v[16:17]
	global_load_dwordx4 v[0:3], v[12:13], off sc1
	global_load_dwordx4 v[16:19], v[28:29], off sc1
	v_add_co_u32_e32 v12, vcc, 0x30000, v12
	global_load_dwordx4 v[4:7], v[4:5], off sc1
	s_nop 0
	v_addc_co_u32_e32 v13, vcc, 0, v13, vcc
	v_add_co_u32_e32 v20, vcc, 0x10000, v28
	global_load_dwordx4 v[8:11], v[8:9], off sc1
	s_nop 0
	v_addc_co_u32_e32 v21, vcc, 0, v29, vcc
	v_add_co_u32_e32 v24, vcc, 0x20000, v28
	global_load_dwordx4 v[12:15], v[12:13], off sc1
	s_nop 0
	v_addc_co_u32_e32 v25, vcc, 0, v29, vcc
	v_add_co_u32_e32 v28, vcc, 0x30000, v28
	global_load_dwordx4 v[20:23], v[20:21], off sc1
	s_nop 0
	v_addc_co_u32_e32 v29, vcc, 0, v29, vcc
	global_load_dwordx4 v[24:27], v[24:25], off sc1
	v_mov_b32_e32 v40, 0
	global_load_dwordx4 v[28:31], v[28:29], off sc1
	v_lshl_add_u64 v[124:125], v[112:113], 0, s[50:51]
	s_mov_b64 s[6:7], 0
	v_mov_b32_e32 v41, v40
	v_mov_b32_e32 v42, v40
	v_mov_b32_e32 v43, v40
	v_mov_b32_e32 v68, v40
	v_mov_b32_e32 v69, v40
	v_mov_b32_e32 v70, v40
	v_mov_b32_e32 v71, v40
	v_mov_b32_e32 v72, v40
	v_mov_b32_e32 v73, v40
	v_mov_b32_e32 v74, v40
	v_mov_b32_e32 v75, v40
	v_mov_b32_e32 v76, v40
	v_mov_b32_e32 v77, v40
	v_mov_b32_e32 v78, v40
	v_mov_b32_e32 v79, v40
	v_mov_b32_e32 v36, v40
	v_mov_b32_e32 v37, v40
	v_mov_b32_e32 v38, v40
	v_mov_b32_e32 v39, v40
	v_mov_b32_e32 v44, v40
	v_mov_b32_e32 v45, v40
	v_mov_b32_e32 v46, v40
	v_mov_b32_e32 v47, v40
	v_mov_b32_e32 v48, v40
	v_mov_b32_e32 v49, v40
	v_mov_b32_e32 v50, v40
	v_mov_b32_e32 v51, v40
	v_mov_b32_e32 v52, v40
	v_mov_b32_e32 v53, v40
	v_mov_b32_e32 v54, v40
	v_mov_b32_e32 v55, v40
	v_mov_b32_e32 v56, v40
	v_mov_b32_e32 v57, v40
	v_mov_b32_e32 v58, v40
	v_mov_b32_e32 v59, v40
	v_mov_b32_e32 v60, v40
	v_mov_b32_e32 v61, v40
	v_mov_b32_e32 v62, v40
	v_mov_b32_e32 v63, v40
	v_mov_b32_e32 v64, v40
	v_mov_b32_e32 v65, v40
	v_mov_b32_e32 v66, v40
	v_mov_b32_e32 v67, v40
	v_mov_b32_e32 v32, v40
	v_mov_b32_e32 v33, v40
	v_mov_b32_e32 v34, v40
	v_mov_b32_e32 v35, v40
	v_mov_b32_e32 v84, v40
	v_mov_b32_e32 v85, v40
	v_mov_b32_e32 v86, v40
	v_mov_b32_e32 v87, v40
	v_mov_b32_e32 v88, v40
	v_mov_b32_e32 v89, v40
	v_mov_b32_e32 v90, v40
	v_mov_b32_e32 v91, v40
	v_mov_b32_e32 v92, v40
	v_mov_b32_e32 v93, v40
	v_mov_b32_e32 v94, v40
	v_mov_b32_e32 v95, v40
	v_mov_b32_e32 v80, v40
	v_mov_b32_e32 v81, v40
	v_mov_b32_e32 v82, v40
	v_mov_b32_e32 v83, v40
.LBB0_250:
	s_barrier
	s_waitcnt vmcnt(7)
	ds_write_b128 v148, v[0:3]
	s_waitcnt vmcnt(5)
	ds_write_b128 v148, v[4:7] offset:5120
	s_waitcnt vmcnt(4)
	ds_write_b128 v148, v[8:11] offset:10240
	s_waitcnt vmcnt(3)
	ds_write_b128 v148, v[12:15] offset:15360
	ds_write_b128 v148, v[16:19] offset:20480
	s_waitcnt vmcnt(2)
	ds_write_b128 v148, v[20:23] offset:25600
	s_waitcnt vmcnt(1)
	ds_write_b128 v148, v[24:27] offset:30720
	s_waitcnt vmcnt(0)
	ds_write_b128 v148, v[28:31] offset:35840
	v_lshl_add_u64 v[0:1], v[116:117], 0, s[6:7]
	v_lshl_add_u64 v[4:5], v[118:119], 0, s[6:7]
	v_lshl_add_u64 v[8:9], v[120:121], 0, s[6:7]
	v_lshl_add_u64 v[12:13], v[122:123], 0, s[6:7]
	v_lshl_add_u64 v[16:17], v[124:125], 0, s[6:7]
	v_lshl_add_u64 v[20:21], v[126:127], 0, s[6:7]
	v_lshl_add_u64 v[24:25], v[128:129], 0, s[6:7]
	v_lshl_add_u64 v[28:29], v[130:131], 0, s[6:7]
	s_waitcnt lgkmcnt(0)
	s_barrier
	global_load_dwordx4 v[0:3], v[0:1], off sc1
	s_nop 0
	global_load_dwordx4 v[4:7], v[4:5], off sc1
	s_nop 0
	global_load_dwordx4 v[8:11], v[8:9], off sc1
	s_nop 0
	global_load_dwordx4 v[12:15], v[12:13], off sc1
	s_nop 0
	global_load_dwordx4 v[16:19], v[16:17], off sc1
	s_nop 0
	global_load_dwordx4 v[20:23], v[20:21], off sc1
	s_nop 0
	global_load_dwordx4 v[24:27], v[24:25], off sc1
	s_nop 0
	global_load_dwordx4 v[28:31], v[28:29], off sc1
	ds_read_b128 v[150:153], v149 offset:20480
	ds_read_b128 v[158:161], v149 offset:23040
	ds_read_b128 v[162:165], v149 offset:25600
	ds_read_b128 v[166:169], v149 offset:28160
	ds_read_b128 v[154:157], v134
	ds_read_b128 v[170:173], v134 offset:2560
	ds_read_b128 v[174:177], v134 offset:5120
	ds_read_b128 v[178:181], v134 offset:7680
	ds_read_b128 v[182:185], v149 offset:20544
	ds_read_b128 v[186:189], v149 offset:23104
	ds_read_b128 v[202:205], v149 offset:25664
	ds_read_b128 v[206:209], v149 offset:28224
	s_add_u32 s6, s6, 0x80
	s_addc_u32 s7, s7, 0
	s_waitcnt lgkmcnt(7)
	v_mfma_f32_16x16x32_bf16 v[32:35], v[150:153], v[154:157], v[32:35]
	v_mfma_f32_16x16x32_bf16 v[64:67], v[158:161], v[154:157], v[64:67]
	v_mfma_f32_16x16x32_bf16 v[60:63], v[162:165], v[154:157], v[60:63]
	v_mfma_f32_16x16x32_bf16 v[56:59], v[166:169], v[154:157], v[56:59]
	ds_read_b128 v[154:157], v134 offset:64
	s_waitcnt lgkmcnt(7)
	v_mfma_f32_16x16x32_bf16 v[52:55], v[150:153], v[170:173], v[52:55]
	v_mfma_f32_16x16x32_bf16 v[48:51], v[158:161], v[170:173], v[48:51]
	v_mfma_f32_16x16x32_bf16 v[44:47], v[162:165], v[170:173], v[44:47]
	v_mfma_f32_16x16x32_bf16 v[36:39], v[166:169], v[170:173], v[36:39]
	ds_read_b128 v[170:173], v134 offset:2624
	s_waitcnt lgkmcnt(7)
	v_mfma_f32_16x16x32_bf16 v[76:79], v[150:153], v[174:177], v[76:79]
	v_mfma_f32_16x16x32_bf16 v[72:75], v[158:161], v[174:177], v[72:75]
	v_mfma_f32_16x16x32_bf16 v[68:71], v[162:165], v[174:177], v[68:71]
	v_mfma_f32_16x16x32_bf16 v[40:43], v[166:169], v[174:177], v[40:43]
	ds_read_b128 v[174:177], v134 offset:5184
	s_waitcnt lgkmcnt(7)
	v_mfma_f32_16x16x32_bf16 v[84:87], v[150:153], v[178:181], v[84:87]
	v_mfma_f32_16x16x32_bf16 v[88:91], v[158:161], v[178:181], v[88:91]
	v_mfma_f32_16x16x32_bf16 v[92:95], v[162:165], v[178:181], v[92:95]
	v_mfma_f32_16x16x32_bf16 v[80:83], v[166:169], v[178:181], v[80:83]
	ds_read_b128 v[178:181], v134 offset:7744
	s_waitcnt lgkmcnt(3)
	v_mfma_f32_16x16x32_bf16 v[32:35], v[182:185], v[154:157], v[32:35]
	v_mfma_f32_16x16x32_bf16 v[64:67], v[186:189], v[154:157], v[64:67]
	v_mfma_f32_16x16x32_bf16 v[60:63], v[202:205], v[154:157], v[60:63]
	v_mfma_f32_16x16x32_bf16 v[56:59], v[206:209], v[154:157], v[56:59]
	s_waitcnt lgkmcnt(2)
	v_mfma_f32_16x16x32_bf16 v[52:55], v[182:185], v[170:173], v[52:55]
	v_mfma_f32_16x16x32_bf16 v[48:51], v[186:189], v[170:173], v[48:51]
	v_mfma_f32_16x16x32_bf16 v[44:47], v[202:205], v[170:173], v[44:47]
	v_mfma_f32_16x16x32_bf16 v[36:39], v[206:209], v[170:173], v[36:39]
	s_waitcnt lgkmcnt(1)
	v_mfma_f32_16x16x32_bf16 v[76:79], v[182:185], v[174:177], v[76:79]
	v_mfma_f32_16x16x32_bf16 v[72:75], v[186:189], v[174:177], v[72:75]
	v_mfma_f32_16x16x32_bf16 v[68:71], v[202:205], v[174:177], v[68:71]
	v_mfma_f32_16x16x32_bf16 v[40:43], v[206:209], v[174:177], v[40:43]
	s_waitcnt lgkmcnt(0)
	v_mfma_f32_16x16x32_bf16 v[84:87], v[182:185], v[178:181], v[84:87]
	v_mfma_f32_16x16x32_bf16 v[88:91], v[186:189], v[178:181], v[88:91]
	v_mfma_f32_16x16x32_bf16 v[92:95], v[202:205], v[178:181], v[92:95]
	v_mfma_f32_16x16x32_bf16 v[80:83], v[206:209], v[178:181], v[80:83]
	s_cmpk_eq_i32 s6, 0x780
	s_cbranch_scc0 .LBB0_250
	s_barrier
	s_waitcnt vmcnt(7)
	ds_write_b128 v148, v[0:3]
	s_waitcnt vmcnt(6)
	ds_write_b128 v148, v[4:7] offset:5120
	s_waitcnt vmcnt(5)
	ds_write_b128 v148, v[8:11] offset:10240
	s_waitcnt vmcnt(4)
	ds_write_b128 v148, v[12:15] offset:15360
	s_waitcnt vmcnt(3)
	ds_write_b128 v148, v[16:19] offset:20480
	s_waitcnt vmcnt(2)
	ds_write_b128 v148, v[20:23] offset:25600
	s_waitcnt vmcnt(1)
	ds_write_b128 v148, v[24:27] offset:30720
	s_waitcnt vmcnt(0)
	ds_write_b128 v148, v[28:31] offset:35840
	s_waitcnt lgkmcnt(0)
	s_barrier
	ds_read_b128 v[0:3], v149 offset:20480
	ds_read_b128 v[4:7], v134
	ds_read_b128 v[12:15], v149 offset:23040
	ds_read_b128 v[20:23], v149 offset:25600
	ds_read_b128 v[28:31], v149 offset:28160
	s_cmpk_lt_u32 s2, 0x800
	s_waitcnt lgkmcnt(3)
	v_mfma_f32_16x16x32_bf16 v[8:11], v[0:3], v[4:7], v[32:35]
	s_cselect_b64 s[6:7], -1, 0
	ds_read_b128 v[128:131], v149 offset:28224
	s_waitcnt lgkmcnt(3)
	v_mfma_f32_16x16x32_bf16 v[16:19], v[12:15], v[4:7], v[64:67]
	s_waitcnt lgkmcnt(2)
	v_mfma_f32_16x16x32_bf16 v[24:27], v[20:23], v[4:7], v[60:63]
	s_waitcnt lgkmcnt(1)
	v_mfma_f32_16x16x32_bf16 v[32:35], v[28:31], v[4:7], v[56:59]
	ds_read_b128 v[4:7], v134 offset:2560
	s_waitcnt lgkmcnt(0)
	v_mfma_f32_16x16x32_bf16 v[64:67], v[0:3], v[4:7], v[52:55]
	v_mfma_f32_16x16x32_bf16 v[116:119], v[12:15], v[4:7], v[48:51]
	v_mfma_f32_16x16x32_bf16 v[120:123], v[20:23], v[4:7], v[44:47]
	v_mfma_f32_16x16x32_bf16 v[36:39], v[28:31], v[4:7], v[36:39]
	ds_read_b128 v[4:7], v134 offset:5120
	s_waitcnt lgkmcnt(0)
	v_mfma_f32_16x16x32_bf16 v[124:127], v[28:31], v[4:7], v[40:43]
	s_nop 2
	ds_read_b128 v[40:43], v134 offset:7680
	v_mfma_f32_16x16x32_bf16 v[76:79], v[0:3], v[4:7], v[76:79]
	v_mfma_f32_16x16x32_bf16 v[72:75], v[12:15], v[4:7], v[72:75]
	v_mfma_f32_16x16x32_bf16 v[68:71], v[20:23], v[4:7], v[68:71]
	s_waitcnt lgkmcnt(0)
	v_mfma_f32_16x16x32_bf16 v[4:7], v[12:15], v[40:43], v[88:91]
	ds_read_b128 v[12:15], v149 offset:20544
	v_mfma_f32_16x16x32_bf16 v[84:87], v[0:3], v[40:43], v[84:87]
	s_nop 0
	ds_read_b128 v[88:91], v149 offset:23104
	v_mfma_f32_16x16x32_bf16 v[0:3], v[20:23], v[40:43], v[92:95]
	ds_read_b128 v[20:23], v134 offset:64
	s_nop 1
	ds_read_b128 v[92:95], v149 offset:25664
	s_waitcnt lgkmcnt(1)
	v_mfma_f32_16x16x32_bf16 v[56:59], v[12:15], v[20:23], v[8:11]
	s_nop 2
	ds_read_b128 v[8:11], v134 offset:2624
	v_mfma_f32_16x16x32_bf16 v[80:83], v[28:31], v[40:43], v[80:83]
	v_mfma_f32_16x16x32_bf16 v[48:51], v[128:131], v[20:23], v[32:35]
	s_waitcnt lgkmcnt(0)
	v_mfma_f32_16x16x32_bf16 v[40:43], v[12:15], v[8:11], v[64:67]
	v_mfma_f32_16x16x32_bf16 v[44:47], v[88:91], v[8:11], v[116:119]
	s_nop 1
	v_add_u32_e32 v64, s3, v133
	v_mfma_f32_16x16x32_bf16 v[32:35], v[92:95], v[8:11], v[120:123]
	v_mfma_f32_16x16x32_bf16 v[36:39], v[128:131], v[8:11], v[36:39]
	ds_read_b128 v[8:11], v134 offset:5184
	v_mfma_f32_16x16x32_bf16 v[52:55], v[92:95], v[20:23], v[24:27]
	s_waitcnt lgkmcnt(0)
	v_mfma_f32_16x16x32_bf16 v[24:27], v[12:15], v[8:11], v[76:79]
	v_mfma_f32_16x16x32_bf16 v[28:31], v[88:91], v[8:11], v[72:75]
	s_nop 2
	ds_read_b128 v[74:77], v134 offset:7744
	v_mfma_f32_16x16x32_bf16 v[60:63], v[88:91], v[20:23], v[16:19]
	v_or_b32_e32 v73, v64, v132
	v_cmp_lt_i32_e32 vcc, s22, v73
	s_and_b64 s[10:11], vcc, s[6:7]
	v_mfma_f32_16x16x32_bf16 v[16:19], v[92:95], v[8:11], v[68:71]
	v_mfma_f32_16x16x32_bf16 v[20:23], v[128:131], v[8:11], v[124:127]
	v_bfe_u32 v8, v64, 6, 6
	v_cvt_f32_ubyte0_e32 v65, v8
	v_mul_f32_e32 v66, v136, v65
	s_waitcnt lgkmcnt(0)
	v_mfma_f32_16x16x32_bf16 v[8:11], v[12:15], v[74:77], v[84:87]
	v_mul_f32_e32 v72, 0.15915494, v66
	v_mfma_f32_16x16x32_bf16 v[12:15], v[88:91], v[74:77], v[4:7]
	s_nop 2
	v_mul_f32_e32 v4, v137, v65
	v_mul_f32_e32 v5, v138, v65
	v_mul_f32_e32 v6, v139, v65
	v_mfma_f32_16x16x32_bf16 v[0:3], v[92:95], v[74:77], v[0:3]
	v_mul_f32_e32 v71, 0.15915494, v4
	v_mul_f32_e32 v70, 0.15915494, v5
	v_mul_f32_e32 v69, 0.15915494, v6
	v_mfma_f32_16x16x32_bf16 v[4:7], v[128:131], v[74:77], v[80:83]
	s_and_saveexec_b64 s[8:9], s[10:11]
	s_cbranch_execz .LBB0_253
	v_cos_f32_e32 v65, v70
	v_sin_f32_e32 v68, v70
	v_cos_f32_e32 v92, v69
	v_sin_f32_e32 v93, v69
	v_cos_f32_e32 v66, v72
	v_sin_f32_e32 v74, v72
	v_sin_f32_e32 v75, v71
	v_cos_f32_e32 v67, v71
	v_mul_f32_e32 v82, v68, v62
	v_mul_f32_e32 v86, v65, v62
	v_mov_b32_e32 v62, v59
	v_mul_f32_e32 v80, v65, v58
	v_mul_f32_e32 v84, v68, v58
	v_pk_mul_f32 v[58:59], v[92:93], v[62:63]
	v_mul_f32_e32 v90, v141, v50
	v_mul_f32_e32 v116, v140, v50
	v_mov_b32_e32 v81, v58
	v_mov_b32_e32 v83, v59
	v_mov_b32_e32 v58, v93
	v_mov_b32_e32 v59, v92
	v_mov_b32_e32 v50, v55
	v_pk_mul_f32 v[76:77], v[74:75], v[60:61]
	v_pk_mul_f32 v[60:61], v[66:67], v[60:61]
	v_pk_mul_f32 v[78:79], v[104:105], v[48:49]
	v_mul_f32_e32 v88, v140, v54
	v_mul_f32_e32 v94, v141, v54
	v_pk_mul_f32 v[58:59], v[58:59], v[62:63]
	v_pk_mul_f32 v[54:55], v[106:107], v[50:51]
	v_pk_mul_f32 v[50:51], v[108:109], v[50:51]
	v_pk_mul_f32 v[48:49], v[102:103], v[48:49]
	v_mov_b32_e32 v85, v58
	v_mov_b32_e32 v87, v59
	v_mov_b32_e32 v89, v54
	v_mov_b32_e32 v91, v55
	v_mov_b32_e32 v95, v50
	v_mov_b32_e32 v117, v51
	v_pk_fma_f32 v[66:67], v[66:67], v[56:57], v[76:77] neg_lo:[0,0,1] neg_hi:[0,0,1]
	v_pk_fma_f32 v[60:61], v[74:75], v[56:57], v[60:61]
	v_pk_fma_f32 v[74:75], v[102:103], v[52:53], v[78:79] neg_lo:[0,0,1] neg_hi:[0,0,1]
	v_pk_add_f32 v[58:59], v[80:81], v[82:83] neg_lo:[0,1] neg_hi:[0,1]
	v_pk_add_f32 v[62:63], v[84:85], v[86:87]
	v_pk_add_f32 v[54:55], v[88:89], v[90:91] neg_lo:[0,1] neg_hi:[0,1]
	v_pk_fma_f32 v[48:49], v[104:105], v[52:53], v[48:49]
	v_pk_add_f32 v[50:51], v[94:95], v[116:117]
	v_mov_b32_e32 v56, v66
	v_mov_b32_e32 v57, v67
	v_mov_b32_e32 v52, v74
	v_mov_b32_e32 v53, v75

.LBB0_296:
	s_and_b32 s2, s16, 7
	v_readlane_b32 s3, v254, 16
	s_lshl_b32 s2, s2, 8
	v_mov_b32_e32 v160, 0
	v_add_u32_e32 v0, s3, v227
	v_add_u32_e32 v0, s2, v0
	v_ashrrev_i32_e32 v1, 31, v0
	v_lshlrev_b64 v[0:1], 11, v[0:1]
	v_readlane_b32 s3, v254, 6
	v_lshl_add_u64 v[202:203], v[198:199], 0, v[0:1]
	s_mov_b64 s[6:7], 0
	v_add_u32_e32 v0, s3, v227
	v_add_u32_e32 v0, s2, v0
	v_ashrrev_i32_e32 v1, 31, v0
	v_lshlrev_b64 v[0:1], 11, v[0:1]
	v_readlane_b32 s3, v254, 7
	v_lshl_add_u64 v[204:205], v[198:199], 0, v[0:1]
	v_mov_b32_e32 v161, v160
	v_add_u32_e32 v0, s3, v227
	v_add_u32_e32 v0, s2, v0
	v_ashrrev_i32_e32 v1, 31, v0
	v_lshlrev_b64 v[0:1], 11, v[0:1]
	v_readlane_b32 s3, v254, 8
	v_lshl_add_u64 v[206:207], v[198:199], 0, v[0:1]
	v_mov_b32_e32 v162, v160
	v_add_u32_e32 v0, s3, v227
	v_add_u32_e32 v0, s2, v0
	v_ashrrev_i32_e32 v1, 31, v0
	v_lshlrev_b64 v[0:1], 11, v[0:1]
	v_readlane_b32 s3, v254, 13
	v_lshl_add_u64 v[208:209], v[198:199], 0, v[0:1]
	v_mov_b32_e32 v163, v160
	v_add_u32_e32 v0, s3, v227
	v_add_u32_e32 v0, s2, v0
	v_ashrrev_i32_e32 v1, 31, v0
	v_lshlrev_b64 v[0:1], 11, v[0:1]
	v_readlane_b32 s3, v254, 14
	v_lshl_add_u64 v[210:211], v[198:199], 0, v[0:1]
	v_mov_b32_e32 v164, v160
	v_add_u32_e32 v0, s3, v227
	v_add_u32_e32 v0, s2, v0
	v_ashrrev_i32_e32 v1, 31, v0
	v_lshlrev_b64 v[0:1], 11, v[0:1]
	v_readlane_b32 s3, v254, 15
	v_lshl_add_u64 v[212:213], v[198:199], 0, v[0:1]
	v_mov_b32_e32 v165, v160
	v_add_u32_e32 v0, s3, v227
	v_add_u32_e32 v0, s2, v0
	v_ashrrev_i32_e32 v1, 31, v0
	v_lshlrev_b64 v[0:1], 11, v[0:1]
	v_lshl_add_u64 v[214:215], v[198:199], 0, v[0:1]
	v_add_u32_e32 v0, s2, v241
	v_ashrrev_i32_e32 v1, 31, v0
	v_lshlrev_b64 v[0:1], 11, v[0:1]
	s_and_b32 s2, s15, 0xf80
	v_lshl_add_u64 v[216:217], v[198:199], 0, v[0:1]
	v_add_u32_e32 v0, s2, v227
	v_ashrrev_i32_e32 v1, 31, v0
	v_lshlrev_b64 v[0:1], 11, v[0:1]
	v_lshl_add_u64 v[218:219], v[200:201], 0, v[0:1]
	v_add_u32_e32 v0, s2, v242
	v_ashrrev_i32_e32 v1, 31, v0
	v_lshlrev_b64 v[0:1], 11, v[0:1]
	v_lshl_add_u64 v[220:221], v[200:201], 0, v[0:1]
	v_add_u32_e32 v0, s2, v243
	v_ashrrev_i32_e32 v1, 31, v0
	v_lshlrev_b64 v[0:1], 11, v[0:1]
	v_lshl_add_u64 v[222:223], v[200:201], 0, v[0:1]
	v_add_u32_e32 v0, s2, v244
	s_and_b32 s2, s17, 7
	v_ashrrev_i32_e32 v1, 31, v0
	s_or_b32 s2, s2, s33
	v_lshlrev_b64 v[0:1], 11, v[0:1]
	s_lshl_b32 s8, s2, 8
	v_lshl_add_u64 v[224:225], v[200:201], 0, v[0:1]
	v_add_u32_e32 v0, s8, v227
	v_ashrrev_i32_e32 v1, 31, v0
	v_lshlrev_b64 v[0:1], 11, v[0:1]
	v_lshl_add_u64 v[24:25], v[192:193], 0, v[0:1]
	s_mov_b32 s2, 0x10000
	v_add_co_u32_e32 v4, vcc, s2, v24
	s_mov_b32 s2, 0x20000
	s_nop 0
	v_addc_co_u32_e32 v5, vcc, 0, v25, vcc
	v_add_co_u32_e32 v8, vcc, s2, v24
	s_mov_b32 s2, 0x30000
	s_nop 0
	v_addc_co_u32_e32 v9, vcc, 0, v25, vcc
	v_add_co_u32_e32 v12, vcc, s2, v24
	s_mov_b32 s2, 0x40000
	s_nop 0
	v_addc_co_u32_e32 v13, vcc, 0, v25, vcc
	v_add_co_u32_e32 v16, vcc, s2, v24
	s_mov_b32 s2, 0x50000
	s_nop 0
	v_addc_co_u32_e32 v17, vcc, 0, v25, vcc
	s_lshl_b32 s3, s17, 4
	v_add_co_u32_e32 v20, vcc, s2, v24
	s_mov_b32 s2, 0x60000
	s_nop 0
	v_addc_co_u32_e32 v21, vcc, 0, v25, vcc
	s_and_b32 s10, s3, 0xf80
	v_add_co_u32_e32 v26, vcc, s2, v24
	v_add_u32_e32 v32, s10, v227
	s_nop 0
	v_addc_co_u32_e32 v27, vcc, 0, v25, vcc
	v_ashrrev_i32_e32 v33, 31, v32
	v_add_co_u32_e32 v28, vcc, 0x70000, v24
	v_lshlrev_b64 v[32:33], 11, v[32:33]
	s_nop 0
	v_addc_co_u32_e32 v29, vcc, 0, v25, vcc
	v_lshl_add_u64 v[40:41], v[194:195], 0, v[32:33]
	v_add_co_u32_e32 v36, vcc, 0x10000, v40
	global_load_dwordx4 v[0:3], v[24:25], off sc1
	s_nop 0
	global_load_dwordx4 v[4:7], v[4:5], off sc1
	v_addc_co_u32_e32 v37, vcc, 0, v41, vcc
	v_add_co_u32_e32 v42, vcc, 0x20000, v40
	global_load_dwordx4 v[8:11], v[8:9], off sc1
	s_nop 0
	global_load_dwordx4 v[12:15], v[12:13], off sc1
	v_addc_co_u32_e32 v43, vcc, 0, v41, vcc
	v_add_co_u32_e32 v44, vcc, 0x30000, v40
	global_load_dwordx4 v[16:19], v[16:17], off sc1
	s_nop 0
	global_load_dwordx4 v[20:23], v[20:21], off sc1
	v_addc_co_u32_e32 v45, vcc, 0, v41, vcc
	global_load_dwordx4 v[24:27], v[26:27], off sc1
	s_nop 0
	global_load_dwordx4 v[28:31], v[28:29], off sc1
	s_nop 0
	global_load_dwordx4 v[32:35], v[40:41], off sc1
	s_nop 0
	global_load_dwordx4 v[36:39], v[36:37], off sc1
	s_nop 0
	global_load_dwordx4 v[40:43], v[42:43], off sc1
	s_nop 0
	global_load_dwordx4 v[44:47], v[44:45], off sc1
	v_mov_b32_e32 v166, v160
	v_mov_b32_e32 v167, v160
	v_mov_b32_e32 v168, v160
	v_mov_b32_e32 v169, v160
	v_mov_b32_e32 v170, v160
	v_mov_b32_e32 v171, v160
	v_mov_b32_e32 v172, v160
	v_mov_b32_e32 v173, v160
	v_mov_b32_e32 v174, v160
	v_mov_b32_e32 v175, v160
	v_mov_b32_e32 v144, v160
	v_mov_b32_e32 v145, v160
	v_mov_b32_e32 v146, v160
	v_mov_b32_e32 v147, v160
	v_mov_b32_e32 v148, v160
	v_mov_b32_e32 v149, v160
	v_mov_b32_e32 v150, v160
	v_mov_b32_e32 v151, v160
	v_mov_b32_e32 v152, v160
	v_mov_b32_e32 v153, v160
	v_mov_b32_e32 v154, v160
	v_mov_b32_e32 v155, v160
	v_mov_b32_e32 v156, v160
	v_mov_b32_e32 v157, v160
	v_mov_b32_e32 v158, v160
	v_mov_b32_e32 v159, v160
	v_mov_b32_e32 v116, v160
	v_mov_b32_e32 v117, v160
	v_mov_b32_e32 v118, v160
	v_mov_b32_e32 v119, v160
	v_mov_b32_e32 v128, v160
	v_mov_b32_e32 v129, v160
	v_mov_b32_e32 v130, v160
	v_mov_b32_e32 v131, v160
	v_mov_b32_e32 v136, v160
	v_mov_b32_e32 v137, v160
	v_mov_b32_e32 v138, v160
	v_mov_b32_e32 v139, v160
	v_mov_b32_e32 v140, v160
	v_mov_b32_e32 v141, v160
	v_mov_b32_e32 v142, v160
	v_mov_b32_e32 v143, v160
	v_mov_b32_e32 v100, v160
	v_mov_b32_e32 v101, v160
	v_mov_b32_e32 v102, v160
	v_mov_b32_e32 v103, v160
	v_mov_b32_e32 v112, v160
	v_mov_b32_e32 v113, v160
	v_mov_b32_e32 v114, v160
	v_mov_b32_e32 v115, v160
	v_mov_b32_e32 v124, v160
	v_mov_b32_e32 v125, v160
	v_mov_b32_e32 v126, v160
	v_mov_b32_e32 v127, v160
	v_mov_b32_e32 v132, v160
	v_mov_b32_e32 v133, v160
	v_mov_b32_e32 v134, v160
	v_mov_b32_e32 v135, v160
	v_mov_b32_e32 v88, v160
	v_mov_b32_e32 v89, v160
	v_mov_b32_e32 v90, v160
	v_mov_b32_e32 v91, v160
	v_mov_b32_e32 v96, v160
	v_mov_b32_e32 v97, v160
	v_mov_b32_e32 v98, v160
	v_mov_b32_e32 v99, v160
	v_mov_b32_e32 v108, v160
	v_mov_b32_e32 v109, v160
	v_mov_b32_e32 v110, v160
	v_mov_b32_e32 v111, v160
	v_mov_b32_e32 v120, v160
	v_mov_b32_e32 v121, v160
	v_mov_b32_e32 v122, v160
	v_mov_b32_e32 v123, v160
	v_mov_b32_e32 v80, v160
	v_mov_b32_e32 v81, v160
	v_mov_b32_e32 v82, v160
	v_mov_b32_e32 v83, v160
	v_mov_b32_e32 v84, v160
	v_mov_b32_e32 v85, v160
	v_mov_b32_e32 v86, v160
	v_mov_b32_e32 v87, v160
	v_mov_b32_e32 v92, v160
	v_mov_b32_e32 v93, v160
	v_mov_b32_e32 v94, v160
	v_mov_b32_e32 v95, v160
	v_mov_b32_e32 v104, v160
	v_mov_b32_e32 v105, v160
	v_mov_b32_e32 v106, v160
	v_mov_b32_e32 v107, v160
	v_mov_b32_e32 v48, v160
	v_mov_b32_e32 v49, v160
	v_mov_b32_e32 v50, v160
	v_mov_b32_e32 v51, v160
	v_mov_b32_e32 v52, v160
	v_mov_b32_e32 v53, v160
	v_mov_b32_e32 v54, v160
	v_mov_b32_e32 v55, v160
	v_mov_b32_e32 v56, v160
	v_mov_b32_e32 v57, v160
	v_mov_b32_e32 v58, v160
	v_mov_b32_e32 v59, v160
	v_mov_b32_e32 v72, v160
	v_mov_b32_e32 v73, v160
	v_mov_b32_e32 v74, v160
	v_mov_b32_e32 v75, v160
	v_mov_b32_e32 v76, v160
	v_mov_b32_e32 v77, v160
	v_mov_b32_e32 v78, v160
	v_mov_b32_e32 v79, v160
	v_mov_b32_e32 v68, v160
	v_mov_b32_e32 v69, v160
	v_mov_b32_e32 v70, v160
	v_mov_b32_e32 v71, v160
	v_mov_b32_e32 v64, v160
	v_mov_b32_e32 v65, v160
	v_mov_b32_e32 v66, v160
	v_mov_b32_e32 v67, v160
	v_mov_b32_e32 v60, v160
	v_mov_b32_e32 v61, v160
	v_mov_b32_e32 v62, v160
	v_mov_b32_e32 v63, v160
.LBB0_297:
	s_barrier
	s_waitcnt vmcnt(11)
	ds_write_b128 v245, v[0:3]
	s_waitcnt vmcnt(10)
	ds_write_b128 v245, v[4:7] offset:5120
	s_waitcnt vmcnt(9)
	ds_write_b128 v245, v[8:11] offset:10240
	s_waitcnt vmcnt(8)
	ds_write_b128 v245, v[12:15] offset:15360
	s_waitcnt vmcnt(7)
	ds_write_b128 v245, v[16:19] offset:20480
	s_waitcnt vmcnt(6)
	ds_write_b128 v245, v[20:23] offset:25600
	s_waitcnt vmcnt(5)
	ds_write_b128 v245, v[24:27] offset:30720
	s_waitcnt vmcnt(4)
	ds_write_b128 v245, v[28:31] offset:35840
	s_waitcnt vmcnt(3)
	ds_write_b128 v245, v[32:35] offset:40960
	s_waitcnt vmcnt(2)
	ds_write_b128 v245, v[36:39] offset:46080
	s_waitcnt vmcnt(1)
	ds_write_b128 v245, v[40:43] offset:51200
	s_waitcnt vmcnt(0)
	ds_write_b128 v245, v[44:47] offset:56320
	v_lshl_add_u64 v[0:1], v[202:203], 0, s[6:7]
	v_lshl_add_u64 v[4:5], v[204:205], 0, s[6:7]
	v_lshl_add_u64 v[8:9], v[206:207], 0, s[6:7]
	v_lshl_add_u64 v[12:13], v[208:209], 0, s[6:7]
	v_lshl_add_u64 v[16:17], v[210:211], 0, s[6:7]
	v_lshl_add_u64 v[20:21], v[212:213], 0, s[6:7]
	v_lshl_add_u64 v[24:25], v[214:215], 0, s[6:7]
	v_lshl_add_u64 v[28:29], v[216:217], 0, s[6:7]
	v_lshl_add_u64 v[32:33], v[218:219], 0, s[6:7]
	v_lshl_add_u64 v[36:37], v[220:221], 0, s[6:7]
	v_lshl_add_u64 v[40:41], v[222:223], 0, s[6:7]
	v_lshl_add_u64 v[44:45], v[224:225], 0, s[6:7]
	s_waitcnt lgkmcnt(0)
	s_barrier
	global_load_dwordx4 v[0:3], v[0:1], off sc1
	s_nop 0
	global_load_dwordx4 v[4:7], v[4:5], off sc1
	s_nop 0
	global_load_dwordx4 v[8:11], v[8:9], off sc1
	s_nop 0
	global_load_dwordx4 v[12:15], v[12:13], off sc1
	s_nop 0
	global_load_dwordx4 v[16:19], v[16:17], off sc1
	s_nop 0
	global_load_dwordx4 v[20:23], v[20:21], off sc1
	s_nop 0
	global_load_dwordx4 v[24:27], v[24:25], off sc1
	s_nop 0
	global_load_dwordx4 v[28:31], v[28:29], off sc1
	s_nop 0
	global_load_dwordx4 v[32:35], v[32:33], off sc1
	s_nop 0
	global_load_dwordx4 v[36:39], v[36:37], off sc1
	s_nop 0
	global_load_dwordx4 v[40:43], v[40:41], off sc1
	s_nop 0
	global_load_dwordx4 v[44:47], v[44:45], off sc1
	ds_read_b128 v[176:179], v246 offset:40960
	ds_read_b128 v[184:187], v246 offset:43520
	ds_read_b128 v[188:191], v246 offset:46080
	ds_read_b128 v[230:233], v246 offset:48640
	ds_read_b128 v[180:183], v238
	ds_read_b128 v[248:251], v238 offset:2560
	s_add_u32 s6, s6, 0x80
	s_addc_u32 s7, s7, 0
	s_waitcnt lgkmcnt(1)
	v_mfma_f32_16x16x32_bf16 v[60:63], v[176:179], v[180:183], v[60:63]
	v_mfma_f32_16x16x32_bf16 v[64:67], v[184:187], v[180:183], v[64:67]
	v_mfma_f32_16x16x32_bf16 v[68:71], v[188:191], v[180:183], v[68:71]
	v_mfma_f32_16x16x32_bf16 v[76:79], v[230:233], v[180:183], v[76:79]
	ds_read_b128 v[180:183], v238 offset:5120
	s_waitcnt lgkmcnt(1)
	v_mfma_f32_16x16x32_bf16 v[72:75], v[176:179], v[248:251], v[72:75]
	v_mfma_f32_16x16x32_bf16 v[56:59], v[184:187], v[248:251], v[56:59]
	v_mfma_f32_16x16x32_bf16 v[52:55], v[188:191], v[248:251], v[52:55]
	v_mfma_f32_16x16x32_bf16 v[48:51], v[230:233], v[248:251], v[48:51]
	ds_read_b128 v[248:251], v238 offset:7680
	s_waitcnt lgkmcnt(1)
	v_mfma_f32_16x16x32_bf16 v[104:107], v[176:179], v[180:183], v[104:107]
	v_mfma_f32_16x16x32_bf16 v[92:95], v[184:187], v[180:183], v[92:95]
	v_mfma_f32_16x16x32_bf16 v[84:87], v[188:191], v[180:183], v[84:87]
	v_mfma_f32_16x16x32_bf16 v[80:83], v[230:233], v[180:183], v[80:83]
	ds_read_b128 v[180:183], v238 offset:10240
	s_waitcnt lgkmcnt(1)
	v_mfma_f32_16x16x32_bf16 v[120:123], v[176:179], v[248:251], v[120:123]
	v_mfma_f32_16x16x32_bf16 v[108:111], v[184:187], v[248:251], v[108:111]
	v_mfma_f32_16x16x32_bf16 v[96:99], v[188:191], v[248:251], v[96:99]
	v_mfma_f32_16x16x32_bf16 v[88:91], v[230:233], v[248:251], v[88:91]
	ds_read_b128 v[248:251], v238 offset:12800
	s_waitcnt lgkmcnt(1)
	v_mfma_f32_16x16x32_bf16 v[132:135], v[176:179], v[180:183], v[132:135]
	v_mfma_f32_16x16x32_bf16 v[124:127], v[184:187], v[180:183], v[124:127]
	v_mfma_f32_16x16x32_bf16 v[112:115], v[188:191], v[180:183], v[112:115]
	v_mfma_f32_16x16x32_bf16 v[100:103], v[230:233], v[180:183], v[100:103]
	ds_read_b128 v[180:183], v238 offset:15360
	s_waitcnt lgkmcnt(1)
	v_mfma_f32_16x16x32_bf16 v[140:143], v[176:179], v[248:251], v[140:143]
	v_mfma_f32_16x16x32_bf16 v[136:139], v[184:187], v[248:251], v[136:139]
	v_mfma_f32_16x16x32_bf16 v[128:131], v[188:191], v[248:251], v[128:131]
	v_mfma_f32_16x16x32_bf16 v[116:119], v[230:233], v[248:251], v[116:119]
	ds_read_b128 v[248:251], v247
	s_waitcnt lgkmcnt(1)
	v_mfma_f32_16x16x32_bf16 v[156:159], v[176:179], v[180:183], v[156:159]
	v_mfma_f32_16x16x32_bf16 v[152:155], v[184:187], v[180:183], v[152:155]
	v_mfma_f32_16x16x32_bf16 v[148:151], v[188:191], v[180:183], v[148:151]
	v_mfma_f32_16x16x32_bf16 v[144:147], v[230:233], v[180:183], v[144:147]
	ds_read_b128 v[180:183], v238 offset:64
	s_waitcnt lgkmcnt(1)
	v_mfma_f32_16x16x32_bf16 v[172:175], v[176:179], v[248:251], v[172:175]
	ds_read_b128 v[176:179], v246 offset:41024
	v_mfma_f32_16x16x32_bf16 v[168:171], v[184:187], v[248:251], v[168:171]
	ds_read_b128 v[184:187], v246 offset:43584
	v_mfma_f32_16x16x32_bf16 v[164:167], v[188:191], v[248:251], v[164:167]
	ds_read_b128 v[188:191], v246 offset:46144
	v_mfma_f32_16x16x32_bf16 v[160:163], v[230:233], v[248:251], v[160:163]
	ds_read_b128 v[230:233], v246 offset:48704
	ds_read_b128 v[248:251], v238 offset:2624
	s_waitcnt lgkmcnt(1)
	v_mfma_f32_16x16x32_bf16 v[60:63], v[176:179], v[180:183], v[60:63]
	v_mfma_f32_16x16x32_bf16 v[64:67], v[184:187], v[180:183], v[64:67]
	v_mfma_f32_16x16x32_bf16 v[68:71], v[188:191], v[180:183], v[68:71]
	v_mfma_f32_16x16x32_bf16 v[76:79], v[230:233], v[180:183], v[76:79]
	ds_read_b128 v[180:183], v238 offset:5184
	s_waitcnt lgkmcnt(1)
	v_mfma_f32_16x16x32_bf16 v[72:75], v[176:179], v[248:251], v[72:75]
	v_mfma_f32_16x16x32_bf16 v[56:59], v[184:187], v[248:251], v[56:59]
	v_mfma_f32_16x16x32_bf16 v[52:55], v[188:191], v[248:251], v[52:55]
	v_mfma_f32_16x16x32_bf16 v[48:51], v[230:233], v[248:251], v[48:51]
	ds_read_b128 v[248:251], v238 offset:7744
	s_waitcnt lgkmcnt(1)
	v_mfma_f32_16x16x32_bf16 v[104:107], v[176:179], v[180:183], v[104:107]
	v_mfma_f32_16x16x32_bf16 v[92:95], v[184:187], v[180:183], v[92:95]
	v_mfma_f32_16x16x32_bf16 v[84:87], v[188:191], v[180:183], v[84:87]
	v_mfma_f32_16x16x32_bf16 v[80:83], v[230:233], v[180:183], v[80:83]
	ds_read_b128 v[180:183], v238 offset:10304
	s_waitcnt lgkmcnt(1)
	v_mfma_f32_16x16x32_bf16 v[120:123], v[176:179], v[248:251], v[120:123]
	v_mfma_f32_16x16x32_bf16 v[108:111], v[184:187], v[248:251], v[108:111]
	v_mfma_f32_16x16x32_bf16 v[96:99], v[188:191], v[248:251], v[96:99]
	v_mfma_f32_16x16x32_bf16 v[88:91], v[230:233], v[248:251], v[88:91]
	ds_read_b128 v[248:251], v238 offset:12864
	s_waitcnt lgkmcnt(1)
	v_mfma_f32_16x16x32_bf16 v[132:135], v[176:179], v[180:183], v[132:135]
	v_mfma_f32_16x16x32_bf16 v[124:127], v[184:187], v[180:183], v[124:127]
	v_mfma_f32_16x16x32_bf16 v[112:115], v[188:191], v[180:183], v[112:115]
	v_mfma_f32_16x16x32_bf16 v[100:103], v[230:233], v[180:183], v[100:103]
	ds_read_b128 v[180:183], v238 offset:15424
	s_waitcnt lgkmcnt(1)
	v_mfma_f32_16x16x32_bf16 v[140:143], v[176:179], v[248:251], v[140:143]
	v_mfma_f32_16x16x32_bf16 v[136:139], v[184:187], v[248:251], v[136:139]
	v_mfma_f32_16x16x32_bf16 v[128:131], v[188:191], v[248:251], v[128:131]
	v_mfma_f32_16x16x32_bf16 v[116:119], v[230:233], v[248:251], v[116:119]
	ds_read_b128 v[248:251], v247 offset:64
	s_waitcnt lgkmcnt(1)
	v_mfma_f32_16x16x32_bf16 v[156:159], v[176:179], v[180:183], v[156:159]
	v_mfma_f32_16x16x32_bf16 v[152:155], v[184:187], v[180:183], v[152:155]
	v_mfma_f32_16x16x32_bf16 v[148:151], v[188:191], v[180:183], v[148:151]
	v_mfma_f32_16x16x32_bf16 v[144:147], v[230:233], v[180:183], v[144:147]
	s_waitcnt lgkmcnt(0)
	v_mfma_f32_16x16x32_bf16 v[172:175], v[176:179], v[248:251], v[172:175]
	v_mfma_f32_16x16x32_bf16 v[168:171], v[184:187], v[248:251], v[168:171]
	v_mfma_f32_16x16x32_bf16 v[164:167], v[188:191], v[248:251], v[164:167]
	v_mfma_f32_16x16x32_bf16 v[160:163], v[230:233], v[248:251], v[160:163]
	s_cmpk_eq_i32 s6, 0x780
	s_cbranch_scc0 .LBB0_297
	s_barrier
	s_waitcnt vmcnt(11)
	ds_write_b128 v245, v[0:3]
	s_waitcnt vmcnt(10)
	ds_write_b128 v245, v[4:7] offset:5120
	s_waitcnt vmcnt(9)
	ds_write_b128 v245, v[8:11] offset:10240
	s_waitcnt vmcnt(8)
	ds_write_b128 v245, v[12:15] offset:15360
	s_waitcnt vmcnt(7)
	ds_write_b128 v245, v[16:19] offset:20480
	s_waitcnt vmcnt(6)
	ds_write_b128 v245, v[20:23] offset:25600
	s_waitcnt vmcnt(5)
	ds_write_b128 v245, v[24:27] offset:30720
	s_waitcnt vmcnt(4)
	ds_write_b128 v245, v[28:31] offset:35840
	s_waitcnt vmcnt(3)
	ds_write_b128 v245, v[32:35] offset:40960
	s_waitcnt vmcnt(2)
	ds_write_b128 v245, v[36:39] offset:46080
	s_waitcnt vmcnt(1)
	ds_write_b128 v245, v[40:43] offset:51200
	s_waitcnt vmcnt(0)
	ds_write_b128 v245, v[44:47] offset:56320
	s_waitcnt lgkmcnt(0)
	s_barrier
	ds_read_b128 v[176:179], v246 offset:40960
	ds_read_b128 v[180:183], v246 offset:43520
	ds_read_b128 v[184:187], v246 offset:46080
	ds_read_b128 v[188:191], v246 offset:48640
	ds_read_b128 v[0:3], v238 offset:2560
	ds_read_b128 v[4:7], v238 offset:5120
	ds_read_b128 v[8:11], v238
	s_add_i32 s2, s10, 0xfffffe00
	s_cmpk_lt_u32 s2, 0x400
	s_waitcnt lgkmcnt(2)
	v_mfma_f32_16x16x32_bf16 v[218:221], v[176:179], v[0:3], v[72:75]
	v_or_b32_e32 v196, s10, v240
	ds_read_b128 v[20:23], v238 offset:15360
	s_waitcnt lgkmcnt(1)
	v_mfma_f32_16x16x32_bf16 v[202:205], v[176:179], v[8:11], v[60:63]
	v_mfma_f32_16x16x32_bf16 v[206:209], v[180:183], v[8:11], v[64:67]
	v_mfma_f32_16x16x32_bf16 v[210:213], v[184:187], v[8:11], v[68:71]
	v_mfma_f32_16x16x32_bf16 v[214:217], v[188:191], v[8:11], v[76:79]
	ds_read_b128 v[8:11], v238 offset:7680
	v_mfma_f32_16x16x32_bf16 v[222:225], v[180:183], v[0:3], v[56:59]
	v_mfma_f32_16x16x32_bf16 v[248:251], v[184:187], v[0:3], v[52:55]
	v_mfma_f32_16x16x32_bf16 v[230:233], v[188:191], v[0:3], v[48:51]
	ds_read_b128 v[0:3], v238 offset:10240
	v_mfma_f32_16x16x32_bf16 v[64:67], v[176:179], v[4:7], v[104:107]
	v_mfma_f32_16x16x32_bf16 v[68:71], v[180:183], v[4:7], v[92:95]
	v_mfma_f32_16x16x32_bf16 v[72:75], v[184:187], v[4:7], v[84:87]
	v_mfma_f32_16x16x32_bf16 v[76:79], v[188:191], v[4:7], v[80:83]
	ds_read_b128 v[4:7], v238 offset:12800
	s_nop 1
	ds_read_b128 v[80:83], v247
	s_waitcnt lgkmcnt(3)
	v_mfma_f32_16x16x32_bf16 v[48:51], v[176:179], v[8:11], v[120:123]
	v_mfma_f32_16x16x32_bf16 v[52:55], v[180:183], v[8:11], v[108:111]
	v_mfma_f32_16x16x32_bf16 v[56:59], v[184:187], v[8:11], v[96:99]
	v_mfma_f32_16x16x32_bf16 v[60:63], v[188:191], v[8:11], v[88:91]
	s_waitcnt lgkmcnt(2)
	v_mfma_f32_16x16x32_bf16 v[32:35], v[176:179], v[0:3], v[132:135]
	v_mfma_f32_16x16x32_bf16 v[36:39], v[180:183], v[0:3], v[124:127]
	v_mfma_f32_16x16x32_bf16 v[40:43], v[184:187], v[0:3], v[112:115]
	v_mfma_f32_16x16x32_bf16 v[44:47], v[188:191], v[0:3], v[100:103]
	s_waitcnt lgkmcnt(1)
	v_mfma_f32_16x16x32_bf16 v[0:3], v[184:187], v[4:7], v[128:131]
	v_mfma_f32_16x16x32_bf16 v[8:11], v[176:179], v[20:23], v[156:159]
	v_mfma_f32_16x16x32_bf16 v[12:15], v[180:183], v[20:23], v[152:155]
	v_mfma_f32_16x16x32_bf16 v[16:19], v[184:187], v[20:23], v[148:151]
	v_mfma_f32_16x16x32_bf16 v[20:23], v[188:191], v[20:23], v[144:147]
	s_waitcnt lgkmcnt(0)
	v_mfma_f32_16x16x32_bf16 v[120:123], v[176:179], v[80:83], v[172:175]
	v_mfma_f32_16x16x32_bf16 v[124:127], v[180:183], v[80:83], v[168:171]
	v_mfma_f32_16x16x32_bf16 v[128:131], v[184:187], v[80:83], v[164:167]
	v_mfma_f32_16x16x32_bf16 v[132:135], v[188:191], v[80:83], v[160:163]
	ds_read_b128 v[144:147], v246 offset:41024
	ds_read_b128 v[148:151], v246 offset:43584
	ds_read_b128 v[152:155], v246 offset:46144
	ds_read_b128 v[156:159], v246 offset:48704
	ds_read_b128 v[80:83], v238 offset:2624
	ds_read_b128 v[84:87], v238 offset:5184
	ds_read_b128 v[88:91], v238 offset:64
	ds_read_b128 v[160:163], v238 offset:7744
	ds_read_b128 v[164:167], v238 offset:10304
	v_mfma_f32_16x16x32_bf16 v[24:27], v[176:179], v[4:7], v[140:143]
	ds_read_b128 v[168:171], v238 offset:12864
	v_mfma_f32_16x16x32_bf16 v[28:31], v[180:183], v[4:7], v[136:139]
	v_mfma_f32_16x16x32_bf16 v[4:7], v[188:191], v[4:7], v[116:119]
	s_waitcnt lgkmcnt(3)
	v_mfma_f32_16x16x32_bf16 v[140:143], v[144:147], v[88:91], v[202:205]
	v_mfma_f32_16x16x32_bf16 v[136:139], v[148:151], v[88:91], v[206:209]
	v_mfma_f32_16x16x32_bf16 v[116:119], v[152:155], v[88:91], v[210:213]
	v_mfma_f32_16x16x32_bf16 v[104:107], v[156:159], v[88:91], v[214:217]
	v_mfma_f32_16x16x32_bf16 v[108:111], v[144:147], v[80:83], v[218:221]
	v_mfma_f32_16x16x32_bf16 v[112:115], v[148:151], v[80:83], v[222:225]
	v_mfma_f32_16x16x32_bf16 v[96:99], v[152:155], v[80:83], v[248:251]
	v_mfma_f32_16x16x32_bf16 v[100:103], v[156:159], v[80:83], v[230:233]
	v_mfma_f32_16x16x32_bf16 v[88:91], v[144:147], v[84:87], v[64:67]
	v_mfma_f32_16x16x32_bf16 v[92:95], v[148:151], v[84:87], v[68:71]
	v_mfma_f32_16x16x32_bf16 v[80:83], v[152:155], v[84:87], v[72:75]
	v_mfma_f32_16x16x32_bf16 v[84:87], v[156:159], v[84:87], v[76:79]
	s_waitcnt lgkmcnt(2)
	v_mfma_f32_16x16x32_bf16 v[72:75], v[144:147], v[160:163], v[48:51]
	v_mfma_f32_16x16x32_bf16 v[76:79], v[148:151], v[160:163], v[52:55]
	v_mfma_f32_16x16x32_bf16 v[64:67], v[152:155], v[160:163], v[56:59]
	v_mfma_f32_16x16x32_bf16 v[68:71], v[156:159], v[160:163], v[60:63]
	ds_read_b128 v[160:163], v238 offset:15424
	s_waitcnt lgkmcnt(2)
	v_mfma_f32_16x16x32_bf16 v[56:59], v[144:147], v[164:167], v[32:35]
	v_mfma_f32_16x16x32_bf16 v[60:63], v[148:151], v[164:167], v[36:39]
	v_mfma_f32_16x16x32_bf16 v[40:43], v[152:155], v[164:167], v[40:43]
	v_mfma_f32_16x16x32_bf16 v[44:47], v[156:159], v[164:167], v[44:47]
	ds_read_b128 v[164:167], v247 offset:64
	s_waitcnt lgkmcnt(2)
	v_mfma_f32_16x16x32_bf16 v[48:51], v[144:147], v[168:171], v[24:27]
	s_waitcnt lgkmcnt(1)
	v_mfma_f32_16x16x32_bf16 v[24:27], v[144:147], v[160:163], v[8:11]
	s_waitcnt lgkmcnt(0)
	v_mfma_f32_16x16x32_bf16 v[8:11], v[144:147], v[164:167], v[120:123]
	s_nop 2
	v_add_u32_e32 v120, s8, v239
	v_mfma_f32_16x16x32_bf16 v[52:55], v[148:151], v[168:171], v[28:31]
	s_cselect_b64 s[8:9], -1, 0
	s_cmpk_lt_u32 s10, 0x400
	s_cselect_b64 s[6:7], -1, 0
	v_mfma_f32_16x16x32_bf16 v[28:31], v[148:151], v[160:163], v[12:15]
	v_mfma_f32_16x16x32_bf16 v[12:15], v[148:151], v[164:167], v[124:127]
	s_nop 2
	v_or_b32_e32 v125, v120, v226
	v_lshlrev_b32_e32 v120, 1, v120
	v_and_b32_e32 v120, 0xfffffe00, v120
	v_add_u32_e32 v124, s14, v120
	v_mov_b64_e32 v[120:121], s[44:45]
	v_mad_i64_i32 v[120:121], s[2:3], v125, s70, v[120:121]
	s_movk_i32 s2, 0x2000
	s_nop 0
	v_cmp_gt_i32_e32 vcc, s2, v125
	s_movk_i32 s2, 0x8f
	v_and_or_b32 v122, v125, s2, v124
	v_mfma_f32_16x16x32_bf16 v[32:35], v[152:155], v[168:171], v[0:3]
	v_ashrrev_i32_e32 v123, 31, v122
	v_lshlrev_b64 v[126:127], 11, v[122:123]
	v_lshlrev_b32_e32 v122, 1, v196
	v_mfma_f32_16x16x32_bf16 v[36:39], v[156:159], v[168:171], v[4:7]
	v_mov_b32_e32 v123, v197
	v_lshl_add_u64 v[122:123], v[120:121], 0, v[122:123]
	v_lshl_add_u64 v[120:121], s[88:89], 0, v[126:127]
	v_mfma_f32_16x16x32_bf16 v[16:19], v[152:155], v[160:163], v[16:19]
	s_and_b64 s[10:11], vcc, s[8:9]
	v_lshl_add_u64 v[120:121], v[196:197], 2, v[120:121]
	v_mfma_f32_16x16x32_bf16 v[20:23], v[156:159], v[160:163], v[20:23]
	v_mfma_f32_16x16x32_bf16 v[0:3], v[152:155], v[164:167], v[128:131]
	v_mfma_f32_16x16x32_bf16 v[4:7], v[156:159], v[164:167], v[132:135]
	s_nop 1
	v_cvt_pk_bf16_f32 v128, v140, v141
	v_cvt_pk_bf16_f32 v129, v142, v143
	global_store_dwordx2 v[122:123], v[128:129], off
	s_and_saveexec_b64 s[12:13], s[10:11]
	s_cbranch_execz .LBB0_300
	s_and_b64 s[2:3], s[6:7], exec
	s_mov_b32 s2, 0x3fff800
	s_cselect_b32 s50, s2, 0x5fff000
	v_lshl_add_u64 v[126:127], v[120:121], 0, s[50:51]
	global_store_dwordx4 v[126:127], v[140:143], off

.LBB0_795:
	v_mov_b32_e32 v2, v228
	s_mov_b64 s[8:9], 0x3000
	v_ashrrev_i32_e32 v0, 6, v2
	v_add_u32_e32 v8, s2, v0
	v_add_u32_e32 v0, 0xffffe000, v8
	v_ashrrev_i32_e32 v0, 12, v0
	v_mad_i32_i24 v0, v0, s12, s12
	v_cmp_lt_i32_e32 vcc, s13, v8
	v_ashrrev_i32_e32 v9, 31, v8
	v_lshlrev_b32_e32 v2, 2, v2
	v_cndmask_b32_e32 v10, 0, v0, vcc
	v_lshlrev_b64 v[0:1], 12, v[8:9]
	v_and_b32_e32 v44, 0xfc, v2
	v_lshl_add_u64 v[0:1], s[88:89], 0, v[0:1]
	v_lshlrev_b32_e32 v196, 2, v44
	v_lshl_add_u64 v[12:13], v[0:1], 0, v[196:197]
	global_load_dwordx4 v[4:7], v[12:13], off offset:2048 sc1
	global_load_dwordx4 v[0:3], v[12:13], off offset:3072 sc1
	v_ashrrev_i32_e32 v11, 31, v10
	v_lshl_add_u64 v[10:11], v[10:11], 2, s[16:17]
	v_lshlrev_b64 v[8:9], 11, v[8:9]
	v_lshl_add_u64 v[18:19], s[40:41], 0, v[8:9]
	s_add_i32 s3, s3, s14
	s_add_i32 s2, s2, s35
	s_cmpk_gt_i32 s3, 0x1ff
	s_waitcnt vmcnt(1)
	v_mov_b32_e32 v16, v5
	s_waitcnt vmcnt(0)
	v_mov_b32_e32 v17, v1
	v_mov_b32_e32 v14, v4
	v_mov_b32_e32 v15, v0
	v_pk_mul_f32 v[16:17], v[16:17], v[16:17]
	s_nop 0
	v_pk_fma_f32 v[14:15], v[14:15], v[14:15], v[16:17]
	v_mov_b32_e32 v16, v6
	v_mov_b32_e32 v17, v2
	v_pk_fma_f32 v[14:15], v[16:17], v[16:17], v[14:15]
	v_mov_b32_e32 v16, v7
	v_mov_b32_e32 v17, v3
	v_pk_fma_f32 v[36:37], v[16:17], v[16:17], v[14:15]
	v_lshl_add_u64 v[14:15], v[10:11], 0, s[8:9]
	s_mov_b64 s[8:9], 0x4000
	v_lshl_add_u64 v[16:17], v[10:11], 0, s[8:9]
	v_lshl_add_u64 v[8:9], v[16:17], 0, v[196:197]
	v_lshl_add_u64 v[10:11], v[14:15], 0, v[196:197]
	global_load_dwordx4 v[20:23], v[12:13], off sc1
	global_load_dwordx4 v[24:27], v196, s[0:1] sc1
	global_load_dwordx4 v[28:31], v[8:9], off sc1
	global_load_dwordx4 v[32:35], v[10:11], off sc1
	s_waitcnt vmcnt(3)
	v_mov_b32_e32 v42, v21
	global_load_dwordx4 v[8:11], v[12:13], off offset:1024 sc1
	v_mov_b32_e32 v40, v20
	v_mov_b32_e32 v12, v22
	v_mov_b32_e32 v38, v23
	s_waitcnt vmcnt(2)
	v_pk_add_f32 v[28:29], v[28:29], 1.0 op_sel_hi:[1,0]
	s_waitcnt vmcnt(0)
	v_mov_b32_e32 v43, v9
	v_mov_b32_e32 v41, v8
	v_pk_mul_f32 v[42:43], v[42:43], v[42:43]
	v_mov_b32_e32 v13, v10
	v_pk_fma_f32 v[40:41], v[40:41], v[40:41], v[42:43]
	v_mov_b32_e32 v39, v11
	v_pk_fma_f32 v[12:13], v[12:13], v[12:13], v[40:41]
	s_nop 0
	v_pk_fma_f32 v[12:13], v[38:39], v[38:39], v[12:13]
	s_nop 0
	v_add_f32_e32 v12, v12, v13
	v_add_f32_e32 v12, v12, v36
	v_add_f32_e32 v12, v12, v37
	s_nop 1
	v_add_f32_dpp v12, v12, v12 quad_perm:[1,0,3,2] row_mask:0xf bank_mask:0xf bound_ctrl:1
	s_nop 1
	v_add_f32_dpp v12, v12, v12 quad_perm:[2,3,0,1] row_mask:0xf bank_mask:0xf bound_ctrl:1
	s_nop 1
	v_add_f32_dpp v12, v12, v12 row_ror:4 row_mask:0xf bank_mask:0xf bound_ctrl:1
	s_nop 1
	v_add_f32_dpp v12, v12, v12 row_ror:8 row_mask:0xf bank_mask:0xf bound_ctrl:1
	s_nop 0
	v_readlane_b32 s10, v12, 16
	v_readlane_b32 s11, v12, 48
	v_readlane_b32 s8, v12, 0
	v_readlane_b32 s9, v12, 32
	v_mov_b32_e32 v12, s10
	v_mov_b32_e32 v13, s11
	v_pk_add_f32 v[12:13], s[8:9], v[12:13]
	s_nop 0
	v_add_f32_e32 v12, v12, v13
	v_fmamk_f32 v12, v12, 0x3a800000, v229
	v_cmp_gt_f32_e32 vcc, s69, v12
	v_mul_f32_e32 v13, 0x4b800000, v12
	s_nop 0
	v_cndmask_b32_e32 v12, v12, v13, vcc
	v_rsq_f32_e32 v12, v12
	s_nop 0
	v_mul_f32_e32 v13, 0x45800000, v12
	v_cndmask_b32_e32 v12, v12, v13, vcc
	v_pk_mul_f32 v[20:21], v[20:21], v[12:13] op_sel_hi:[1,0]
	v_pk_mul_f32 v[22:23], v[22:23], v[12:13] op_sel_hi:[1,0]
	v_pk_mul_f32 v[20:21], v[24:25], v[20:21]
	v_pk_mul_f32 v[22:23], v[26:27], v[22:23]
	v_pk_add_f32 v[24:25], v[30:31], 1.0 op_sel_hi:[1,0]
	v_pk_fma_f32 v[20:21], v[28:29], v[20:21], v[32:33]
	v_pk_fma_f32 v[22:23], v[24:25], v[22:23], v[34:35]
	v_cvt_pk_bf16_f32 v20, v20, v21
	v_cvt_pk_bf16_f32 v21, v22, v23
	v_lshlrev_b32_e32 v22, 1, v44
	v_mov_b32_e32 v23, v197
	v_lshl_add_u64 v[18:19], v[18:19], 0, v[22:23]
	global_store_dwordx2 v[18:19], v[20:21], off
	v_or_b32_e32 v20, 0x400, v196
	v_mov_b32_e32 v21, v197
	v_lshl_add_u64 v[24:25], v[16:17], 0, v[20:21]
	v_lshl_add_u64 v[28:29], v[14:15], 0, v[20:21]
	global_load_dwordx4 v[20:23], v196, s[0:1] offset:1024 sc1
	s_nop 0
	global_load_dwordx4 v[24:27], v[24:25], off sc1
	s_nop 0
	global_load_dwordx4 v[28:31], v[28:29], off sc1
	v_pk_mul_f32 v[8:9], v[8:9], v[12:13] op_sel_hi:[1,0]
	v_pk_mul_f32 v[10:11], v[10:11], v[12:13] op_sel_hi:[1,0]
	v_pk_mul_f32 v[4:5], v[4:5], v[12:13] op_sel_hi:[1,0]
	v_pk_mul_f32 v[6:7], v[6:7], v[12:13] op_sel_hi:[1,0]
	v_pk_mul_f32 v[0:1], v[0:1], v[12:13] op_sel_hi:[1,0]
	v_pk_mul_f32 v[2:3], v[2:3], v[12:13] op_sel_hi:[1,0]
	s_waitcnt vmcnt(2)
	v_pk_mul_f32 v[8:9], v[8:9], v[20:21]
	s_waitcnt vmcnt(1)
	v_pk_add_f32 v[20:21], v[24:25], 1.0 op_sel_hi:[1,0]
	v_pk_mul_f32 v[10:11], v[10:11], v[22:23]
	s_waitcnt vmcnt(0)
	v_pk_fma_f32 v[8:9], v[8:9], v[20:21], v[28:29]
	v_pk_add_f32 v[20:21], v[26:27], 1.0 op_sel_hi:[1,0]
	v_cvt_pk_bf16_f32 v8, v8, v9
	v_pk_fma_f32 v[10:11], v[10:11], v[20:21], v[30:31]
	s_nop 0
	v_cvt_pk_bf16_f32 v9, v10, v11
	global_store_dwordx2 v[18:19], v[8:9], off offset:512
	v_or_b32_e32 v8, 0x800, v196
	v_mov_b32_e32 v9, v197
	v_lshl_add_u64 v[20:21], v[16:17], 0, v[8:9]
	v_lshl_add_u64 v[24:25], v[14:15], 0, v[8:9]
	global_load_dwordx4 v[8:11], v196, s[0:1] offset:2048 sc1
	s_nop 0
	global_load_dwordx4 v[20:23], v[20:21], off sc1
	s_nop 0
	global_load_dwordx4 v[24:27], v[24:25], off sc1
	s_waitcnt vmcnt(2)
	v_pk_mul_f32 v[4:5], v[4:5], v[8:9]
	s_waitcnt vmcnt(1)
	v_pk_add_f32 v[8:9], v[20:21], 1.0 op_sel_hi:[1,0]
	v_pk_mul_f32 v[6:7], v[6:7], v[10:11]
	s_waitcnt vmcnt(0)
	v_pk_fma_f32 v[4:5], v[4:5], v[8:9], v[24:25]
	v_pk_add_f32 v[8:9], v[22:23], 1.0 op_sel_hi:[1,0]
	v_cvt_pk_bf16_f32 v4, v4, v5
	v_pk_fma_f32 v[6:7], v[6:7], v[8:9], v[26:27]
	s_nop 0
	v_cvt_pk_bf16_f32 v5, v6, v7
	global_store_dwordx2 v[18:19], v[4:5], off offset:1024
	v_or_b32_e32 v4, 0xc00, v196
	v_mov_b32_e32 v5, v197
	v_lshl_add_u64 v[8:9], v[16:17], 0, v[4:5]
	v_lshl_add_u64 v[14:15], v[14:15], 0, v[4:5]
	global_load_dwordx4 v[4:7], v196, s[0:1] offset:3072 sc1
	s_nop 0
	global_load_dwordx4 v[8:11], v[8:9], off sc1
	s_nop 0
	global_load_dwordx4 v[14:17], v[14:15], off sc1
	s_waitcnt vmcnt(2)
	v_pk_mul_f32 v[0:1], v[0:1], v[4:5]
	s_waitcnt vmcnt(1)
	v_pk_add_f32 v[4:5], v[8:9], 1.0 op_sel_hi:[1,0]
	v_pk_mul_f32 v[2:3], v[2:3], v[6:7]
	s_waitcnt vmcnt(0)
	v_pk_fma_f32 v[0:1], v[0:1], v[4:5], v[14:15]
	v_pk_add_f32 v[4:5], v[10:11], 1.0 op_sel_hi:[1,0]
	v_cvt_pk_bf16_f32 v0, v0, v1
	v_pk_fma_f32 v[2:3], v[2:3], v[4:5], v[16:17]
	s_nop 0
	v_cvt_pk_bf16_f32 v1, v2, v3
	global_store_dwordx2 v[18:19], v[0:1], off offset:1536
	s_cbranch_scc0 .LBB0_795

.LBB0_827:
	s_or_b64 exec, exec, s[14:15]
	s_waitcnt vmcnt(0)
	v_readlane_b32 s2, v255, 12
	s_cmp_lg_u32 s2, 0
	s_cbranch_scc1 .Lxb_noinv_5_1
	buffer_inv sc1

.Lxb_local_5:
	s_mov_b64 s[12:13], exec
	v_mbcnt_lo_u32_b32 v0, s12, 0
	v_mbcnt_hi_u32_b32 v0, s13, v0
	v_cmp_eq_u32_e32 vcc, 0, v0
	s_waitcnt vmcnt(0)
	v_readlane_b32 s2, v255, 12
	s_cmp_lg_u32 s2, 0
	s_cbranch_scc1 .Lxb_noinv_5_0
	buffer_inv sc1
.Lxb_noinv_5_0:
	s_and_saveexec_b64 s[14:15], vcc
	s_cbranch_execz .LBB0_847
	s_bcnt1_i32_b64 s2, s[12:13]
	v_mov_b32_e32 v0, s2
	global_atomic_add v236, v0, s[10:11] offset:1024

.LBB0_850:
	s_and_b32 s2, s11, 7
	v_readlane_b32 s3, v254, 16
	s_lshl_b32 s2, s2, 8
	v_mov_b32_e32 v160, 0
	v_add_u32_e32 v0, s3, v239
	v_add_u32_e32 v0, s2, v0
	v_ashrrev_i32_e32 v1, 31, v0
	v_lshlrev_b64 v[0:1], 11, v[0:1]
	v_readlane_b32 s3, v254, 6
	v_lshl_add_u64 v[192:193], v[204:205], 0, v[0:1]
	s_mov_b64 s[8:9], 0
	v_add_u32_e32 v0, s3, v239
	v_add_u32_e32 v0, s2, v0
	v_ashrrev_i32_e32 v1, 31, v0
	v_lshlrev_b64 v[0:1], 11, v[0:1]
	v_readlane_b32 s3, v254, 7
	v_lshl_add_u64 v[194:195], v[204:205], 0, v[0:1]
	v_mov_b32_e32 v161, v160
	v_add_u32_e32 v0, s3, v239
	v_add_u32_e32 v0, s2, v0
	v_ashrrev_i32_e32 v1, 31, v0
	v_lshlrev_b64 v[0:1], 11, v[0:1]
	v_readlane_b32 s3, v254, 8
	v_lshl_add_u64 v[208:209], v[204:205], 0, v[0:1]
	v_mov_b32_e32 v162, v160
	v_add_u32_e32 v0, s3, v239
	v_add_u32_e32 v0, s2, v0
	v_ashrrev_i32_e32 v1, 31, v0
	v_lshlrev_b64 v[0:1], 11, v[0:1]
	v_readlane_b32 s3, v254, 13
	v_lshl_add_u64 v[210:211], v[204:205], 0, v[0:1]
	v_mov_b32_e32 v163, v160
	v_add_u32_e32 v0, s3, v239
	v_add_u32_e32 v0, s2, v0
	v_ashrrev_i32_e32 v1, 31, v0
	v_lshlrev_b64 v[0:1], 11, v[0:1]
	v_readlane_b32 s3, v254, 14
	v_lshl_add_u64 v[212:213], v[204:205], 0, v[0:1]
	v_mov_b32_e32 v164, v160
	v_add_u32_e32 v0, s3, v239
	v_add_u32_e32 v0, s2, v0
	v_ashrrev_i32_e32 v1, 31, v0
	v_lshlrev_b64 v[0:1], 11, v[0:1]
	v_readlane_b32 s3, v254, 15
	v_lshl_add_u64 v[214:215], v[204:205], 0, v[0:1]
	v_mov_b32_e32 v165, v160
	v_add_u32_e32 v0, s3, v239
	v_add_u32_e32 v0, s2, v0
	v_ashrrev_i32_e32 v1, 31, v0
	v_lshlrev_b64 v[0:1], 11, v[0:1]
	v_readlane_b32 s3, v254, 17
	v_lshl_add_u64 v[216:217], v[204:205], 0, v[0:1]
	v_mov_b32_e32 v166, v160
	v_add_u32_e32 v0, s3, v239
	v_add_u32_e32 v0, s2, v0
	v_ashrrev_i32_e32 v1, 31, v0
	v_lshlrev_b64 v[0:1], 11, v[0:1]
	s_and_b32 s2, s10, 0x1f80
	v_lshl_add_u64 v[218:219], v[204:205], 0, v[0:1]
	v_add_u32_e32 v0, s2, v239
	v_ashrrev_i32_e32 v1, 31, v0
	v_lshlrev_b64 v[0:1], 11, v[0:1]
	v_lshl_add_u64 v[220:221], v[206:207], 0, v[0:1]
	v_add_u32_e32 v0, s2, v242
	v_ashrrev_i32_e32 v1, 31, v0
	v_lshlrev_b64 v[0:1], 11, v[0:1]
	v_lshl_add_u64 v[222:223], v[206:207], 0, v[0:1]
	v_add_u32_e32 v0, s2, v243
	v_ashrrev_i32_e32 v1, 31, v0
	v_lshlrev_b64 v[0:1], 11, v[0:1]
	v_lshl_add_u64 v[224:225], v[206:207], 0, v[0:1]
	v_add_u32_e32 v0, s2, v244
	s_and_b32 s2, s12, 7
	v_ashrrev_i32_e32 v1, 31, v0
	s_or_b32 s2, s2, s33
	v_lshlrev_b64 v[0:1], 11, v[0:1]
	s_lshl_b32 s13, s2, 8
	v_lshl_add_u64 v[226:227], v[206:207], 0, v[0:1]
	v_add_u32_e32 v0, s13, v239
	v_ashrrev_i32_e32 v1, 31, v0
	v_lshlrev_b64 v[0:1], 11, v[0:1]
	v_lshl_add_u64 v[24:25], v[198:199], 0, v[0:1]
	s_mov_b32 s2, 0x10000
	v_add_co_u32_e32 v4, vcc, s2, v24
	s_mov_b32 s2, 0x20000
	s_nop 0
	v_addc_co_u32_e32 v5, vcc, 0, v25, vcc
	v_add_co_u32_e32 v8, vcc, s2, v24
	s_mov_b32 s2, 0x30000
	s_nop 0
	v_addc_co_u32_e32 v9, vcc, 0, v25, vcc
	v_add_co_u32_e32 v12, vcc, s2, v24
	s_mov_b32 s2, 0x40000
	s_nop 0
	v_addc_co_u32_e32 v13, vcc, 0, v25, vcc
	v_add_co_u32_e32 v16, vcc, s2, v24
	s_mov_b32 s2, 0x50000
	s_nop 0
	v_addc_co_u32_e32 v17, vcc, 0, v25, vcc
	s_lshl_b32 s3, s12, 4
	v_add_co_u32_e32 v20, vcc, s2, v24
	s_mov_b32 s2, 0x60000
	s_nop 0
	v_addc_co_u32_e32 v21, vcc, 0, v25, vcc
	s_and_b32 s14, s3, 0x1f80
	v_add_co_u32_e32 v26, vcc, s2, v24
	v_add_u32_e32 v32, s14, v239
	s_nop 0
	v_addc_co_u32_e32 v27, vcc, 0, v25, vcc
	v_ashrrev_i32_e32 v33, 31, v32
	v_add_co_u32_e32 v28, vcc, 0x70000, v24
	v_lshlrev_b64 v[32:33], 11, v[32:33]
	s_nop 0
	v_addc_co_u32_e32 v29, vcc, 0, v25, vcc
	v_lshl_add_u64 v[40:41], v[200:201], 0, v[32:33]
	v_add_co_u32_e32 v36, vcc, 0x10000, v40
	global_load_dwordx4 v[0:3], v[24:25], off sc1
	s_nop 0
	global_load_dwordx4 v[4:7], v[4:5], off sc1
	v_addc_co_u32_e32 v37, vcc, 0, v41, vcc
	v_add_co_u32_e32 v42, vcc, 0x20000, v40
	global_load_dwordx4 v[8:11], v[8:9], off sc1
	s_nop 0
	global_load_dwordx4 v[12:15], v[12:13], off sc1
	v_addc_co_u32_e32 v43, vcc, 0, v41, vcc
	v_add_co_u32_e32 v44, vcc, 0x30000, v40
	global_load_dwordx4 v[16:19], v[16:17], off sc1
	s_nop 0
	global_load_dwordx4 v[20:23], v[20:21], off sc1
	v_addc_co_u32_e32 v45, vcc, 0, v41, vcc
	global_load_dwordx4 v[24:27], v[26:27], off sc1
	s_nop 0
	global_load_dwordx4 v[28:31], v[28:29], off sc1
	s_nop 0
	global_load_dwordx4 v[32:35], v[40:41], off sc1
	s_nop 0
	global_load_dwordx4 v[36:39], v[36:37], off sc1
	s_nop 0
	global_load_dwordx4 v[40:43], v[42:43], off sc1
	s_nop 0
	global_load_dwordx4 v[44:47], v[44:45], off sc1
	v_mov_b32_e32 v167, v160
	v_mov_b32_e32 v168, v160
	v_mov_b32_e32 v169, v160
	v_mov_b32_e32 v170, v160
	v_mov_b32_e32 v171, v160
	v_mov_b32_e32 v172, v160
	v_mov_b32_e32 v173, v160
	v_mov_b32_e32 v174, v160
	v_mov_b32_e32 v175, v160
	v_mov_b32_e32 v144, v160
	v_mov_b32_e32 v145, v160
	v_mov_b32_e32 v146, v160
	v_mov_b32_e32 v147, v160
	v_mov_b32_e32 v148, v160
	v_mov_b32_e32 v149, v160
	v_mov_b32_e32 v150, v160
	v_mov_b32_e32 v151, v160
	v_mov_b32_e32 v152, v160
	v_mov_b32_e32 v153, v160
	v_mov_b32_e32 v154, v160
	v_mov_b32_e32 v155, v160
	v_mov_b32_e32 v156, v160
	v_mov_b32_e32 v157, v160
	v_mov_b32_e32 v158, v160
	v_mov_b32_e32 v159, v160
	v_mov_b32_e32 v116, v160
	v_mov_b32_e32 v117, v160
	v_mov_b32_e32 v118, v160
	v_mov_b32_e32 v119, v160
	v_mov_b32_e32 v128, v160
	v_mov_b32_e32 v129, v160
	v_mov_b32_e32 v130, v160
	v_mov_b32_e32 v131, v160
	v_mov_b32_e32 v136, v160
	v_mov_b32_e32 v137, v160
	v_mov_b32_e32 v138, v160
	v_mov_b32_e32 v139, v160
	v_mov_b32_e32 v140, v160
	v_mov_b32_e32 v141, v160
	v_mov_b32_e32 v142, v160
	v_mov_b32_e32 v143, v160
	v_mov_b32_e32 v100, v160
	v_mov_b32_e32 v101, v160
	v_mov_b32_e32 v102, v160
	v_mov_b32_e32 v103, v160
	v_mov_b32_e32 v112, v160
	v_mov_b32_e32 v113, v160
	v_mov_b32_e32 v114, v160
	v_mov_b32_e32 v115, v160
	v_mov_b32_e32 v124, v160
	v_mov_b32_e32 v125, v160
	v_mov_b32_e32 v126, v160
	v_mov_b32_e32 v127, v160
	v_mov_b32_e32 v132, v160
	v_mov_b32_e32 v133, v160
	v_mov_b32_e32 v134, v160
	v_mov_b32_e32 v135, v160
	v_mov_b32_e32 v76, v160
	v_mov_b32_e32 v77, v160
	v_mov_b32_e32 v78, v160
	v_mov_b32_e32 v79, v160
	v_mov_b32_e32 v96, v160
	v_mov_b32_e32 v97, v160
	v_mov_b32_e32 v98, v160
	v_mov_b32_e32 v99, v160
	v_mov_b32_e32 v108, v160
	v_mov_b32_e32 v109, v160
	v_mov_b32_e32 v110, v160
	v_mov_b32_e32 v111, v160
	v_mov_b32_e32 v120, v160
	v_mov_b32_e32 v121, v160
	v_mov_b32_e32 v122, v160
	v_mov_b32_e32 v123, v160
	v_mov_b32_e32 v60, v160
	v_mov_b32_e32 v61, v160
	v_mov_b32_e32 v62, v160
	v_mov_b32_e32 v63, v160
	v_mov_b32_e32 v68, v160
	v_mov_b32_e32 v69, v160
	v_mov_b32_e32 v70, v160
	v_mov_b32_e32 v71, v160
	v_mov_b32_e32 v92, v160
	v_mov_b32_e32 v93, v160
	v_mov_b32_e32 v94, v160
	v_mov_b32_e32 v95, v160
	v_mov_b32_e32 v104, v160
	v_mov_b32_e32 v105, v160
	v_mov_b32_e32 v106, v160
	v_mov_b32_e32 v107, v160
	v_mov_b32_e32 v52, v160
	v_mov_b32_e32 v53, v160
	v_mov_b32_e32 v54, v160
	v_mov_b32_e32 v55, v160
	v_mov_b32_e32 v56, v160
	v_mov_b32_e32 v57, v160
	v_mov_b32_e32 v58, v160
	v_mov_b32_e32 v59, v160
	v_mov_b32_e32 v64, v160
	v_mov_b32_e32 v65, v160
	v_mov_b32_e32 v66, v160
	v_mov_b32_e32 v67, v160
	v_mov_b32_e32 v84, v160
	v_mov_b32_e32 v85, v160
	v_mov_b32_e32 v86, v160
	v_mov_b32_e32 v87, v160
	v_mov_b32_e32 v88, v160
	v_mov_b32_e32 v89, v160
	v_mov_b32_e32 v90, v160
	v_mov_b32_e32 v91, v160
	v_mov_b32_e32 v80, v160
	v_mov_b32_e32 v81, v160
	v_mov_b32_e32 v82, v160
	v_mov_b32_e32 v83, v160
	v_mov_b32_e32 v72, v160
	v_mov_b32_e32 v73, v160
	v_mov_b32_e32 v74, v160
	v_mov_b32_e32 v75, v160
	v_mov_b32_e32 v48, v160
	v_mov_b32_e32 v49, v160
	v_mov_b32_e32 v50, v160
	v_mov_b32_e32 v51, v160
.LBB0_851:
	s_waitcnt vmcnt(63) expcnt(7) lgkmcnt(15)
	s_barrier
	s_waitcnt vmcnt(11)
	ds_write_b128 v245, v[0:3]
	s_waitcnt vmcnt(10)
	ds_write_b128 v245, v[4:7] offset:5120
	s_waitcnt vmcnt(9)
	ds_write_b128 v245, v[8:11] offset:10240
	s_waitcnt vmcnt(8)
	ds_write_b128 v245, v[12:15] offset:15360
	s_waitcnt vmcnt(7)
	ds_write_b128 v245, v[16:19] offset:20480
	s_waitcnt vmcnt(6)
	ds_write_b128 v245, v[20:23] offset:25600
	s_waitcnt vmcnt(5)
	ds_write_b128 v245, v[24:27] offset:30720
	s_waitcnt vmcnt(4)
	ds_write_b128 v245, v[28:31] offset:35840
	s_waitcnt vmcnt(3)
	ds_write_b128 v245, v[32:35] offset:40960
	s_waitcnt vmcnt(2)
	ds_write_b128 v245, v[36:39] offset:46080
	s_waitcnt vmcnt(1)
	ds_write_b128 v245, v[40:43] offset:51200
	s_waitcnt vmcnt(0)
	ds_write_b128 v245, v[44:47] offset:56320
	v_lshl_add_u64 v[0:1], v[192:193], 0, s[8:9]
	v_lshl_add_u64 v[4:5], v[194:195], 0, s[8:9]
	v_lshl_add_u64 v[8:9], v[208:209], 0, s[8:9]
	v_lshl_add_u64 v[12:13], v[210:211], 0, s[8:9]
	v_lshl_add_u64 v[16:17], v[212:213], 0, s[8:9]
	v_lshl_add_u64 v[20:21], v[214:215], 0, s[8:9]
	v_lshl_add_u64 v[24:25], v[216:217], 0, s[8:9]
	v_lshl_add_u64 v[28:29], v[218:219], 0, s[8:9]
	v_lshl_add_u64 v[32:33], v[220:221], 0, s[8:9]
	v_lshl_add_u64 v[36:37], v[222:223], 0, s[8:9]
	v_lshl_add_u64 v[40:41], v[224:225], 0, s[8:9]
	v_lshl_add_u64 v[44:45], v[226:227], 0, s[8:9]
	s_waitcnt lgkmcnt(0)
	s_barrier
	global_load_dwordx4 v[0:3], v[0:1], off sc1
	s_nop 0
	global_load_dwordx4 v[4:7], v[4:5], off sc1
	s_nop 0
	global_load_dwordx4 v[8:11], v[8:9], off sc1
	s_nop 0
	global_load_dwordx4 v[12:15], v[12:13], off sc1
	s_nop 0
	global_load_dwordx4 v[16:19], v[16:17], off sc1
	s_nop 0
	global_load_dwordx4 v[20:23], v[20:21], off sc1
	s_nop 0
	global_load_dwordx4 v[24:27], v[24:25], off sc1
	s_nop 0
	global_load_dwordx4 v[28:31], v[28:29], off sc1
	s_nop 0
	global_load_dwordx4 v[32:35], v[32:33], off sc1
	s_nop 0
	global_load_dwordx4 v[36:39], v[36:37], off sc1
	s_nop 0
	global_load_dwordx4 v[40:43], v[40:41], off sc1
	s_nop 0
	global_load_dwordx4 v[44:47], v[44:45], off sc1
	ds_read_b128 v[176:179], v246 offset:40960
	ds_read_b128 v[184:187], v246 offset:43520
	ds_read_b128 v[188:191], v246 offset:46080
	ds_read_b128 v[230:233], v246 offset:48640
	ds_read_b128 v[180:183], v241
	ds_read_b128 v[248:251], v241 offset:2560
	s_add_u32 s8, s8, 0x80
	s_addc_u32 s9, s9, 0
	s_waitcnt lgkmcnt(1)
	v_mfma_f32_16x16x32_bf16 v[48:51], v[176:179], v[180:183], v[48:51]
	v_mfma_f32_16x16x32_bf16 v[72:75], v[184:187], v[180:183], v[72:75]
	v_mfma_f32_16x16x32_bf16 v[80:83], v[188:191], v[180:183], v[80:83]
	v_mfma_f32_16x16x32_bf16 v[88:91], v[230:233], v[180:183], v[88:91]
	ds_read_b128 v[180:183], v241 offset:5120
	s_waitcnt lgkmcnt(1)
	v_mfma_f32_16x16x32_bf16 v[84:87], v[176:179], v[248:251], v[84:87]
	v_mfma_f32_16x16x32_bf16 v[64:67], v[184:187], v[248:251], v[64:67]
	v_mfma_f32_16x16x32_bf16 v[56:59], v[188:191], v[248:251], v[56:59]
	v_mfma_f32_16x16x32_bf16 v[52:55], v[230:233], v[248:251], v[52:55]
	ds_read_b128 v[248:251], v241 offset:7680
	s_waitcnt lgkmcnt(1)
	v_mfma_f32_16x16x32_bf16 v[104:107], v[176:179], v[180:183], v[104:107]
	v_mfma_f32_16x16x32_bf16 v[92:95], v[184:187], v[180:183], v[92:95]
	v_mfma_f32_16x16x32_bf16 v[68:71], v[188:191], v[180:183], v[68:71]
	v_mfma_f32_16x16x32_bf16 v[60:63], v[230:233], v[180:183], v[60:63]
	ds_read_b128 v[180:183], v241 offset:10240
	s_waitcnt lgkmcnt(1)
	v_mfma_f32_16x16x32_bf16 v[120:123], v[176:179], v[248:251], v[120:123]
	v_mfma_f32_16x16x32_bf16 v[108:111], v[184:187], v[248:251], v[108:111]
	v_mfma_f32_16x16x32_bf16 v[96:99], v[188:191], v[248:251], v[96:99]
	v_mfma_f32_16x16x32_bf16 v[76:79], v[230:233], v[248:251], v[76:79]
	ds_read_b128 v[248:251], v241 offset:12800
	s_waitcnt lgkmcnt(1)
	v_mfma_f32_16x16x32_bf16 v[132:135], v[176:179], v[180:183], v[132:135]
	v_mfma_f32_16x16x32_bf16 v[124:127], v[184:187], v[180:183], v[124:127]
	v_mfma_f32_16x16x32_bf16 v[112:115], v[188:191], v[180:183], v[112:115]
	v_mfma_f32_16x16x32_bf16 v[100:103], v[230:233], v[180:183], v[100:103]
	ds_read_b128 v[180:183], v241 offset:15360
	s_waitcnt lgkmcnt(1)
	v_mfma_f32_16x16x32_bf16 v[140:143], v[176:179], v[248:251], v[140:143]
	v_mfma_f32_16x16x32_bf16 v[136:139], v[184:187], v[248:251], v[136:139]
	v_mfma_f32_16x16x32_bf16 v[128:131], v[188:191], v[248:251], v[128:131]
	v_mfma_f32_16x16x32_bf16 v[116:119], v[230:233], v[248:251], v[116:119]
	ds_read_b128 v[248:251], v247
	s_waitcnt lgkmcnt(1)
	v_mfma_f32_16x16x32_bf16 v[156:159], v[176:179], v[180:183], v[156:159]
	v_mfma_f32_16x16x32_bf16 v[152:155], v[184:187], v[180:183], v[152:155]
	v_mfma_f32_16x16x32_bf16 v[148:151], v[188:191], v[180:183], v[148:151]
	v_mfma_f32_16x16x32_bf16 v[144:147], v[230:233], v[180:183], v[144:147]
	ds_read_b128 v[180:183], v241 offset:64
	s_waitcnt lgkmcnt(1)
	v_mfma_f32_16x16x32_bf16 v[172:175], v[176:179], v[248:251], v[172:175]
	ds_read_b128 v[176:179], v246 offset:41024
	v_mfma_f32_16x16x32_bf16 v[168:171], v[184:187], v[248:251], v[168:171]
	ds_read_b128 v[184:187], v246 offset:43584
	v_mfma_f32_16x16x32_bf16 v[164:167], v[188:191], v[248:251], v[164:167]
	ds_read_b128 v[188:191], v246 offset:46144
	v_mfma_f32_16x16x32_bf16 v[160:163], v[230:233], v[248:251], v[160:163]
	ds_read_b128 v[230:233], v246 offset:48704
	ds_read_b128 v[248:251], v241 offset:2624
	s_waitcnt lgkmcnt(1)
	v_mfma_f32_16x16x32_bf16 v[48:51], v[176:179], v[180:183], v[48:51]
	v_mfma_f32_16x16x32_bf16 v[72:75], v[184:187], v[180:183], v[72:75]
	v_mfma_f32_16x16x32_bf16 v[80:83], v[188:191], v[180:183], v[80:83]
	v_mfma_f32_16x16x32_bf16 v[88:91], v[230:233], v[180:183], v[88:91]
	ds_read_b128 v[180:183], v241 offset:5184
	s_waitcnt lgkmcnt(1)
	v_mfma_f32_16x16x32_bf16 v[84:87], v[176:179], v[248:251], v[84:87]
	v_mfma_f32_16x16x32_bf16 v[64:67], v[184:187], v[248:251], v[64:67]
	v_mfma_f32_16x16x32_bf16 v[56:59], v[188:191], v[248:251], v[56:59]
	v_mfma_f32_16x16x32_bf16 v[52:55], v[230:233], v[248:251], v[52:55]
	ds_read_b128 v[248:251], v241 offset:7744
	s_waitcnt lgkmcnt(1)
	v_mfma_f32_16x16x32_bf16 v[104:107], v[176:179], v[180:183], v[104:107]
	v_mfma_f32_16x16x32_bf16 v[92:95], v[184:187], v[180:183], v[92:95]
	v_mfma_f32_16x16x32_bf16 v[68:71], v[188:191], v[180:183], v[68:71]
	v_mfma_f32_16x16x32_bf16 v[60:63], v[230:233], v[180:183], v[60:63]
	ds_read_b128 v[180:183], v241 offset:10304
	s_waitcnt lgkmcnt(1)
	v_mfma_f32_16x16x32_bf16 v[120:123], v[176:179], v[248:251], v[120:123]
	v_mfma_f32_16x16x32_bf16 v[108:111], v[184:187], v[248:251], v[108:111]
	v_mfma_f32_16x16x32_bf16 v[96:99], v[188:191], v[248:251], v[96:99]
	v_mfma_f32_16x16x32_bf16 v[76:79], v[230:233], v[248:251], v[76:79]
	ds_read_b128 v[248:251], v241 offset:12864
	s_waitcnt lgkmcnt(1)
	v_mfma_f32_16x16x32_bf16 v[132:135], v[176:179], v[180:183], v[132:135]
	v_mfma_f32_16x16x32_bf16 v[124:127], v[184:187], v[180:183], v[124:127]
	v_mfma_f32_16x16x32_bf16 v[112:115], v[188:191], v[180:183], v[112:115]
	v_mfma_f32_16x16x32_bf16 v[100:103], v[230:233], v[180:183], v[100:103]
	ds_read_b128 v[180:183], v241 offset:15424
	s_waitcnt lgkmcnt(1)
	v_mfma_f32_16x16x32_bf16 v[140:143], v[176:179], v[248:251], v[140:143]
	v_mfma_f32_16x16x32_bf16 v[136:139], v[184:187], v[248:251], v[136:139]
	v_mfma_f32_16x16x32_bf16 v[128:131], v[188:191], v[248:251], v[128:131]
	v_mfma_f32_16x16x32_bf16 v[116:119], v[230:233], v[248:251], v[116:119]
	ds_read_b128 v[248:251], v247 offset:64
	s_waitcnt lgkmcnt(1)
	v_mfma_f32_16x16x32_bf16 v[156:159], v[176:179], v[180:183], v[156:159]
	v_mfma_f32_16x16x32_bf16 v[152:155], v[184:187], v[180:183], v[152:155]
	v_mfma_f32_16x16x32_bf16 v[148:151], v[188:191], v[180:183], v[148:151]
	v_mfma_f32_16x16x32_bf16 v[144:147], v[230:233], v[180:183], v[144:147]
	s_waitcnt lgkmcnt(0)
	v_mfma_f32_16x16x32_bf16 v[172:175], v[176:179], v[248:251], v[172:175]
	v_mfma_f32_16x16x32_bf16 v[168:171], v[184:187], v[248:251], v[168:171]
	v_mfma_f32_16x16x32_bf16 v[164:167], v[188:191], v[248:251], v[164:167]
	v_mfma_f32_16x16x32_bf16 v[160:163], v[230:233], v[248:251], v[160:163]
	s_cmpk_eq_i32 s8, 0x780
	s_cbranch_scc0 .LBB0_851
	s_barrier
	s_waitcnt vmcnt(11)
	ds_write_b128 v245, v[0:3]
	s_waitcnt vmcnt(10)
	ds_write_b128 v245, v[4:7] offset:5120
	s_waitcnt vmcnt(9)
	ds_write_b128 v245, v[8:11] offset:10240
	s_waitcnt vmcnt(8)
	ds_write_b128 v245, v[12:15] offset:15360
	s_waitcnt vmcnt(7)
	ds_write_b128 v245, v[16:19] offset:20480
	s_waitcnt vmcnt(6)
	ds_write_b128 v245, v[20:23] offset:25600
	s_waitcnt vmcnt(5)
	ds_write_b128 v245, v[24:27] offset:30720
	s_waitcnt vmcnt(4)
	ds_write_b128 v245, v[28:31] offset:35840
	s_waitcnt vmcnt(3)
	ds_write_b128 v245, v[32:35] offset:40960
	s_waitcnt vmcnt(2)
	ds_write_b128 v245, v[36:39] offset:46080
	s_waitcnt vmcnt(1)
	ds_write_b128 v245, v[40:43] offset:51200
	s_waitcnt vmcnt(0)
	ds_write_b128 v245, v[44:47] offset:56320
	s_waitcnt lgkmcnt(0)
	s_barrier
	ds_read_b128 v[208:211], v246 offset:40960
	ds_read_b128 v[212:215], v246 offset:43520
	ds_read_b128 v[216:219], v246 offset:46080
	ds_read_b128 v[220:223], v246 offset:48640
	ds_read_b128 v[0:3], v241
	ds_read_b128 v[4:7], v241 offset:2560
	ds_read_b128 v[8:11], v241 offset:5120
	ds_read_b128 v[12:15], v241 offset:12800
	v_or_b32_e32 v196, s14, v238
	s_waitcnt lgkmcnt(3)
	v_mfma_f32_16x16x32_bf16 v[180:183], v[208:211], v[0:3], v[48:51]
	s_add_i32 s12, s12, s53
	s_add_i32 s11, s11, s53
	v_mfma_f32_16x16x32_bf16 v[184:187], v[212:215], v[0:3], v[72:75]
	v_mfma_f32_16x16x32_bf16 v[188:191], v[216:219], v[0:3], v[80:83]
	v_mfma_f32_16x16x32_bf16 v[192:195], v[220:223], v[0:3], v[88:91]
	ds_read_b128 v[0:3], v241 offset:7680
	s_waitcnt lgkmcnt(3)
	v_mfma_f32_16x16x32_bf16 v[80:83], v[208:211], v[4:7], v[84:87]
	v_mfma_f32_16x16x32_bf16 v[84:87], v[212:215], v[4:7], v[64:67]
	v_mfma_f32_16x16x32_bf16 v[88:91], v[216:219], v[4:7], v[56:59]
	v_mfma_f32_16x16x32_bf16 v[176:179], v[220:223], v[4:7], v[52:55]
	ds_read_b128 v[4:7], v241 offset:10240
	s_waitcnt lgkmcnt(3)
	v_mfma_f32_16x16x32_bf16 v[72:75], v[212:215], v[8:11], v[92:95]
	s_waitcnt lgkmcnt(1)
	v_mfma_f32_16x16x32_bf16 v[56:59], v[220:223], v[0:3], v[76:79]
	s_nop 0
	ds_read_b128 v[92:95], v247
	s_nop 0
	ds_read_b128 v[76:79], v241 offset:15360
	v_mfma_f32_16x16x32_bf16 v[64:67], v[208:211], v[8:11], v[104:107]
	v_mfma_f32_16x16x32_bf16 v[68:71], v[216:219], v[8:11], v[68:71]
	v_mfma_f32_16x16x32_bf16 v[60:63], v[220:223], v[8:11], v[60:63]
	v_mfma_f32_16x16x32_bf16 v[44:47], v[208:211], v[0:3], v[120:123]
	s_waitcnt lgkmcnt(2)
	v_mfma_f32_16x16x32_bf16 v[28:31], v[208:211], v[4:7], v[132:135]
	v_mfma_f32_16x16x32_bf16 v[32:35], v[212:215], v[4:7], v[124:127]
	v_mfma_f32_16x16x32_bf16 v[36:39], v[216:219], v[4:7], v[112:115]
	v_mfma_f32_16x16x32_bf16 v[40:43], v[220:223], v[4:7], v[100:103]
	v_mfma_f32_16x16x32_bf16 v[4:7], v[212:215], v[12:15], v[136:139]
	v_mfma_f32_16x16x32_bf16 v[8:11], v[216:219], v[12:15], v[128:131]
	s_waitcnt lgkmcnt(0)
	v_mfma_f32_16x16x32_bf16 v[16:19], v[208:211], v[76:79], v[156:159]
	v_mfma_f32_16x16x32_bf16 v[20:23], v[212:215], v[76:79], v[152:155]
	v_mfma_f32_16x16x32_bf16 v[24:27], v[216:219], v[76:79], v[148:151]
	v_mfma_f32_16x16x32_bf16 v[120:123], v[220:223], v[76:79], v[144:147]
	v_mfma_f32_16x16x32_bf16 v[124:127], v[208:211], v[92:95], v[172:175]
	v_mfma_f32_16x16x32_bf16 v[128:131], v[212:215], v[92:95], v[168:171]
	v_mfma_f32_16x16x32_bf16 v[132:135], v[216:219], v[92:95], v[164:167]
	v_mfma_f32_16x16x32_bf16 v[136:139], v[220:223], v[92:95], v[160:163]
	ds_read_b128 v[148:151], v246 offset:41024
	ds_read_b128 v[152:155], v246 offset:43584
	ds_read_b128 v[156:159], v246 offset:46144
	ds_read_b128 v[160:163], v246 offset:48704
	ds_read_b128 v[76:79], v241 offset:64
	ds_read_b128 v[92:95], v241 offset:2624
	ds_read_b128 v[164:167], v241 offset:5184
	ds_read_b128 v[168:171], v241 offset:7744
	ds_read_b128 v[172:175], v241 offset:10304
	v_mfma_f32_16x16x32_bf16 v[48:51], v[212:215], v[0:3], v[108:111]
	v_mfma_f32_16x16x32_bf16 v[52:55], v[216:219], v[0:3], v[96:99]
	v_mfma_f32_16x16x32_bf16 v[0:3], v[208:211], v[12:15], v[140:143]
	v_mfma_f32_16x16x32_bf16 v[12:15], v[220:223], v[12:15], v[116:119]
	s_waitcnt lgkmcnt(4)
	v_mfma_f32_16x16x32_bf16 v[144:147], v[148:151], v[76:79], v[180:183]
	v_mfma_f32_16x16x32_bf16 v[116:119], v[152:155], v[76:79], v[184:187]
	v_mfma_f32_16x16x32_bf16 v[140:143], v[156:159], v[76:79], v[188:191]
	v_mfma_f32_16x16x32_bf16 v[112:115], v[160:163], v[76:79], v[192:195]
	s_waitcnt lgkmcnt(3)
	v_mfma_f32_16x16x32_bf16 v[108:111], v[148:151], v[92:95], v[80:83]
	v_mfma_f32_16x16x32_bf16 v[100:103], v[152:155], v[92:95], v[84:87]
	v_mfma_f32_16x16x32_bf16 v[104:107], v[156:159], v[92:95], v[88:91]
	v_mfma_f32_16x16x32_bf16 v[96:99], v[160:163], v[92:95], v[176:179]
	s_waitcnt lgkmcnt(2)
	v_mfma_f32_16x16x32_bf16 v[92:95], v[148:151], v[164:167], v[64:67]
	v_mfma_f32_16x16x32_bf16 v[84:87], v[152:155], v[164:167], v[72:75]
	v_mfma_f32_16x16x32_bf16 v[88:91], v[156:159], v[164:167], v[68:71]
	v_mfma_f32_16x16x32_bf16 v[80:83], v[160:163], v[164:167], v[60:63]
	ds_read_b128 v[164:167], v241 offset:12864
	s_waitcnt lgkmcnt(2)
	v_mfma_f32_16x16x32_bf16 v[76:79], v[148:151], v[168:171], v[44:47]
	v_mfma_f32_16x16x32_bf16 v[68:71], v[152:155], v[168:171], v[48:51]
	v_mfma_f32_16x16x32_bf16 v[72:75], v[156:159], v[168:171], v[52:55]
	v_mfma_f32_16x16x32_bf16 v[64:67], v[160:163], v[168:171], v[56:59]
	ds_read_b128 v[168:171], v241 offset:15424
	s_waitcnt lgkmcnt(2)
	v_mfma_f32_16x16x32_bf16 v[60:63], v[148:151], v[172:175], v[28:31]
	s_waitcnt lgkmcnt(0)
	v_mfma_f32_16x16x32_bf16 v[28:31], v[148:151], v[168:171], v[16:19]
	v_mfma_f32_16x16x32_bf16 v[16:19], v[160:163], v[168:171], v[120:123]
	s_nop 2
	v_mul_f32_e32 v123, 0xbfb8aa3b, v144
	v_mfma_f32_16x16x32_bf16 v[52:55], v[152:155], v[172:175], v[32:35]
	v_exp_f32_e32 v123, v123
	v_add_u32_e32 v122, s13, v240
	v_lshl_add_u64 v[120:121], v[202:203], 0, v[196:197]
	v_mfma_f32_16x16x32_bf16 v[56:59], v[156:159], v[172:175], v[36:39]
	v_add_f32_e32 v123, 1.0, v123
	v_mfma_f32_16x16x32_bf16 v[48:51], v[160:163], v[172:175], v[40:43]
	ds_read_b128 v[172:175], v247 offset:64
	v_mfma_f32_16x16x32_bf16 v[32:35], v[160:163], v[164:167], v[12:15]
	s_waitcnt lgkmcnt(0)
	v_mfma_f32_16x16x32_bf16 v[12:15], v[148:151], v[172:175], v[124:127]
	s_nop 2
	v_rcp_f32_e32 v126, v123
	v_mul_f32_e32 v123, 0xbfb8aa3b, v145
	v_exp_f32_e32 v123, v123
	v_mfma_f32_16x16x32_bf16 v[36:39], v[152:155], v[164:167], v[4:7]
	v_mad_i64_i32 v[124:125], s[2:3], v122, s46, v[120:121]
	v_add_f32_e32 v123, 1.0, v123
	v_rcp_f32_e32 v127, v123
	v_mul_f32_e32 v123, 0xbfb8aa3b, v146
	v_exp_f32_e32 v123, v123
	v_mfma_f32_16x16x32_bf16 v[4:7], v[152:155], v[172:175], v[128:131]
	v_mul_f32_e64 v126, v144, v126
	v_mul_f32_e64 v127, v145, v127
	v_add_f32_e32 v123, 1.0, v123
	v_rcp_f32_e32 v128, v123
	v_mul_f32_e32 v123, 0xbfb8aa3b, v147
	v_exp_f32_e32 v123, v123
	v_pk_mul_f32 v[126:127], v[140:141], v[126:127]
	v_mfma_f32_16x16x32_bf16 v[44:47], v[148:151], v[164:167], v[0:3]
	v_cvt_pk_bf16_f32 v126, v126, v127
	v_add_f32_e32 v123, 1.0, v123
	v_rcp_f32_e32 v129, v123
	v_mul_f32_e32 v123, 0xbfb8aa3b, v116
	v_exp_f32_e32 v123, v123
	v_mfma_f32_16x16x32_bf16 v[40:43], v[156:159], v[164:167], v[8:11]
	v_mul_f32_e64 v128, v146, v128
	v_mul_f32_e64 v129, v147, v129
	v_add_f32_e32 v123, 1.0, v123
	v_pk_mul_f32 v[128:129], v[142:143], v[128:129]
	v_mfma_f32_16x16x32_bf16 v[24:27], v[156:159], v[168:171], v[24:27]
	v_cvt_pk_bf16_f32 v127, v128, v129
	global_store_dwordx2 v[124:125], v[126:127], off
	v_rcp_f32_e32 v126, v123
	v_mul_f32_e32 v123, 0xbfb8aa3b, v117
	v_exp_f32_e32 v123, v123
	v_mfma_f32_16x16x32_bf16 v[20:23], v[152:155], v[168:171], v[20:23]
	v_add_f32_e32 v123, 1.0, v123
	v_rcp_f32_e32 v127, v123
	v_mfma_f32_16x16x32_bf16 v[8:11], v[156:159], v[172:175], v[132:135]
	v_mul_f32_e64 v116, v116, v126
	v_mul_f32_e64 v117, v117, v127
	v_pk_mul_f32 v[112:113], v[112:113], v[116:117]
	v_mfma_f32_16x16x32_bf16 v[0:3], v[160:163], v[172:175], v[136:139]
	v_cvt_pk_bf16_f32 v112, v112, v113
	v_mul_f32_e32 v113, 0xbfb8aa3b, v118
	v_exp_f32_e32 v113, v113
	s_nop 0
	v_add_f32_e32 v113, 1.0, v113
	v_rcp_f32_e32 v116, v113
	v_mul_f32_e32 v113, 0xbfb8aa3b, v119
	v_exp_f32_e32 v113, v113
	s_nop 0
	v_add_f32_e32 v113, 1.0, v113
	v_rcp_f32_e32 v117, v113
	s_nop 0
	v_pk_mul_f32 v[116:117], v[118:119], v[116:117]
	s_nop 0
	v_pk_mul_f32 v[114:115], v[114:115], v[116:117]
	s_nop 0
	v_cvt_pk_bf16_f32 v113, v114, v115
	v_mul_f32_e32 v114, 0xbfb8aa3b, v108
	v_mul_f32_e32 v115, 0xbfb8aa3b, v109
	v_exp_f32_e32 v114, v114
	v_exp_f32_e32 v115, v115
	global_store_dwordx2 v[124:125], v[112:113], off offset:32
	v_or_b32_e32 v112, 16, v122
	v_add_f32_e32 v114, 1.0, v114
	v_add_f32_e32 v115, 1.0, v115
	v_rcp_f32_e32 v114, v114
	v_rcp_f32_e32 v115, v115
	v_mad_i64_i32 v[112:113], s[2:3], v112, s46, v[120:121]
	v_pk_mul_f32 v[108:109], v[108:109], v[114:115]
	s_nop 0
	v_pk_mul_f32 v[104:105], v[104:105], v[108:109]
	s_nop 0
	v_cvt_pk_bf16_f32 v104, v104, v105
	v_mul_f32_e32 v105, 0xbfb8aa3b, v110
	v_exp_f32_e32 v105, v105
	s_nop 0
	v_add_f32_e32 v105, 1.0, v105
	v_rcp_f32_e32 v108, v105
	v_mul_f32_e32 v105, 0xbfb8aa3b, v111
	v_exp_f32_e32 v105, v105
	s_nop 0
	v_add_f32_e32 v105, 1.0, v105
	v_rcp_f32_e32 v109, v105
	s_nop 0
	v_pk_mul_f32 v[108:109], v[110:111], v[108:109]
	s_nop 0
	v_pk_mul_f32 v[106:107], v[106:107], v[108:109]
	s_nop 0
	v_cvt_pk_bf16_f32 v105, v106, v107
	global_store_dwordx2 v[112:113], v[104:105], off
	v_mul_f32_e32 v104, 0xbfb8aa3b, v100
	v_mul_f32_e32 v105, 0xbfb8aa3b, v101
	v_exp_f32_e32 v104, v104
	v_exp_f32_e32 v105, v105
	v_add_f32_e32 v104, 1.0, v104
	v_add_f32_e32 v105, 1.0, v105
	v_rcp_f32_e32 v104, v104
	v_rcp_f32_e32 v105, v105
	s_nop 0
	v_pk_mul_f32 v[100:101], v[100:101], v[104:105]
	s_nop 0
	v_pk_mul_f32 v[96:97], v[96:97], v[100:101]
	s_nop 0
	v_cvt_pk_bf16_f32 v96, v96, v97
	v_mul_f32_e32 v97, 0xbfb8aa3b, v102
	v_exp_f32_e32 v97, v97
	s_nop 0
	v_add_f32_e32 v97, 1.0, v97
	v_rcp_f32_e32 v100, v97
	v_mul_f32_e32 v97, 0xbfb8aa3b, v103
	v_exp_f32_e32 v97, v97
	s_nop 0
	v_add_f32_e32 v97, 1.0, v97
	v_rcp_f32_e32 v101, v97
	s_nop 0
	v_pk_mul_f32 v[100:101], v[102:103], v[100:101]
	s_nop 0
	v_pk_mul_f32 v[98:99], v[98:99], v[100:101]
	s_nop 0
	v_cvt_pk_bf16_f32 v97, v98, v99
	v_mul_f32_e32 v98, 0xbfb8aa3b, v92
	v_mul_f32_e32 v99, 0xbfb8aa3b, v93
	v_exp_f32_e32 v98, v98
	v_exp_f32_e32 v99, v99
	global_store_dwordx2 v[112:113], v[96:97], off offset:32
	v_or_b32_e32 v96, 32, v122
	v_add_f32_e32 v98, 1.0, v98
	v_add_f32_e32 v99, 1.0, v99
	v_rcp_f32_e32 v98, v98
	v_rcp_f32_e32 v99, v99
	v_mad_i64_i32 v[96:97], s[2:3], v96, s46, v[120:121]
	v_pk_mul_f32 v[92:93], v[92:93], v[98:99]
	s_nop 0
	v_pk_mul_f32 v[88:89], v[88:89], v[92:93]
	s_nop 0
	v_cvt_pk_bf16_f32 v88, v88, v89
	v_mul_f32_e32 v89, 0xbfb8aa3b, v94
	v_exp_f32_e32 v89, v89
	s_nop 0
	v_add_f32_e32 v89, 1.0, v89
	v_rcp_f32_e32 v92, v89
	v_mul_f32_e32 v89, 0xbfb8aa3b, v95
	v_exp_f32_e32 v89, v89
	s_nop 0
	v_add_f32_e32 v89, 1.0, v89
	v_rcp_f32_e32 v93, v89
	s_nop 0
	v_pk_mul_f32 v[92:93], v[94:95], v[92:93]
	s_nop 0
	v_pk_mul_f32 v[90:91], v[90:91], v[92:93]
	s_nop 0
	v_cvt_pk_bf16_f32 v89, v90, v91
	global_store_dwordx2 v[96:97], v[88:89], off
	v_mul_f32_e32 v88, 0xbfb8aa3b, v84
	v_mul_f32_e32 v89, 0xbfb8aa3b, v85
	v_exp_f32_e32 v88, v88
	v_exp_f32_e32 v89, v89
	v_add_f32_e32 v88, 1.0, v88
	v_add_f32_e32 v89, 1.0, v89
	v_rcp_f32_e32 v88, v88
	v_rcp_f32_e32 v89, v89
	s_nop 0
	v_pk_mul_f32 v[84:85], v[84:85], v[88:89]
	s_nop 0
	v_pk_mul_f32 v[80:81], v[80:81], v[84:85]
	s_nop 0
	v_cvt_pk_bf16_f32 v80, v80, v81
	v_mul_f32_e32 v81, 0xbfb8aa3b, v86
	v_exp_f32_e32 v81, v81
	s_nop 0
	v_add_f32_e32 v81, 1.0, v81
	v_rcp_f32_e32 v84, v81
	v_mul_f32_e32 v81, 0xbfb8aa3b, v87
	v_exp_f32_e32 v81, v81
	s_nop 0
	v_add_f32_e32 v81, 1.0, v81
	v_rcp_f32_e32 v85, v81
	s_nop 0
	v_pk_mul_f32 v[84:85], v[86:87], v[84:85]
	s_nop 0
	v_pk_mul_f32 v[82:83], v[82:83], v[84:85]
	s_nop 0
	v_cvt_pk_bf16_f32 v81, v82, v83
	v_mul_f32_e32 v82, 0xbfb8aa3b, v76
	v_mul_f32_e32 v83, 0xbfb8aa3b, v77
	v_exp_f32_e32 v82, v82
	v_exp_f32_e32 v83, v83
	global_store_dwordx2 v[96:97], v[80:81], off offset:32
	v_or_b32_e32 v80, 48, v122
	v_add_f32_e32 v82, 1.0, v82
	v_add_f32_e32 v83, 1.0, v83
	v_rcp_f32_e32 v82, v82
	v_rcp_f32_e32 v83, v83
	v_mad_i64_i32 v[80:81], s[2:3], v80, s46, v[120:121]
	v_pk_mul_f32 v[76:77], v[76:77], v[82:83]
	s_nop 0
	v_pk_mul_f32 v[72:73], v[72:73], v[76:77]
	s_nop 0
	v_cvt_pk_bf16_f32 v72, v72, v73
	v_mul_f32_e32 v73, 0xbfb8aa3b, v78
	v_exp_f32_e32 v73, v73
	s_nop 0
	v_add_f32_e32 v73, 1.0, v73
	v_rcp_f32_e32 v76, v73
	v_mul_f32_e32 v73, 0xbfb8aa3b, v79
	v_exp_f32_e32 v73, v73
	s_nop 0
	v_add_f32_e32 v73, 1.0, v73
	v_rcp_f32_e32 v77, v73
	s_nop 0
	v_pk_mul_f32 v[76:77], v[78:79], v[76:77]
	s_nop 0
	v_pk_mul_f32 v[74:75], v[74:75], v[76:77]
	s_nop 0
	v_cvt_pk_bf16_f32 v73, v74, v75
	global_store_dwordx2 v[80:81], v[72:73], off
	v_mul_f32_e32 v72, 0xbfb8aa3b, v68
	v_mul_f32_e32 v73, 0xbfb8aa3b, v69
	v_exp_f32_e32 v72, v72
	v_exp_f32_e32 v73, v73
	v_add_f32_e32 v72, 1.0, v72
	v_add_f32_e32 v73, 1.0, v73
	v_rcp_f32_e32 v72, v72
	v_rcp_f32_e32 v73, v73
	s_nop 0
	v_pk_mul_f32 v[68:69], v[68:69], v[72:73]
	s_nop 0
	v_pk_mul_f32 v[64:65], v[64:65], v[68:69]
	s_nop 0
	v_cvt_pk_bf16_f32 v64, v64, v65
	v_mul_f32_e32 v65, 0xbfb8aa3b, v70
	v_exp_f32_e32 v65, v65
	s_nop 0
	v_add_f32_e32 v65, 1.0, v65
	v_rcp_f32_e32 v68, v65
	v_mul_f32_e32 v65, 0xbfb8aa3b, v71
	v_exp_f32_e32 v65, v65
	s_nop 0
	v_add_f32_e32 v65, 1.0, v65
	v_rcp_f32_e32 v69, v65
	s_nop 0
	v_pk_mul_f32 v[68:69], v[70:71], v[68:69]
	s_nop 0
	v_pk_mul_f32 v[66:67], v[66:67], v[68:69]
	s_nop 0
	v_cvt_pk_bf16_f32 v65, v66, v67
	v_mul_f32_e32 v66, 0xbfb8aa3b, v60
	v_mul_f32_e32 v67, 0xbfb8aa3b, v61
	v_exp_f32_e32 v66, v66
	v_exp_f32_e32 v67, v67
	global_store_dwordx2 v[80:81], v[64:65], off offset:32
	v_or_b32_e32 v64, 64, v122
	v_add_f32_e32 v66, 1.0, v66
	v_add_f32_e32 v67, 1.0, v67
	v_rcp_f32_e32 v66, v66
	v_rcp_f32_e32 v67, v67
	v_mad_i64_i32 v[64:65], s[2:3], v64, s46, v[120:121]
	v_pk_mul_f32 v[60:61], v[60:61], v[66:67]
	s_nop 0
	v_pk_mul_f32 v[56:57], v[56:57], v[60:61]
	s_nop 0
	v_cvt_pk_bf16_f32 v56, v56, v57
	v_mul_f32_e32 v57, 0xbfb8aa3b, v62
	v_exp_f32_e32 v57, v57
	s_nop 0
	v_add_f32_e32 v57, 1.0, v57
	v_rcp_f32_e32 v60, v57
	v_mul_f32_e32 v57, 0xbfb8aa3b, v63
	v_exp_f32_e32 v57, v57
	s_nop 0
	v_add_f32_e32 v57, 1.0, v57
	v_rcp_f32_e32 v61, v57
	s_nop 0
	v_pk_mul_f32 v[60:61], v[62:63], v[60:61]
	s_nop 0
	v_pk_mul_f32 v[58:59], v[58:59], v[60:61]
	s_nop 0
	v_cvt_pk_bf16_f32 v57, v58, v59
	global_store_dwordx2 v[64:65], v[56:57], off
	v_mul_f32_e32 v56, 0xbfb8aa3b, v52
	v_mul_f32_e32 v57, 0xbfb8aa3b, v53
	v_exp_f32_e32 v56, v56
	v_exp_f32_e32 v57, v57
	v_add_f32_e32 v56, 1.0, v56
	v_add_f32_e32 v57, 1.0, v57
	v_rcp_f32_e32 v56, v56
	v_rcp_f32_e32 v57, v57
	s_nop 0
	v_pk_mul_f32 v[52:53], v[52:53], v[56:57]
	s_nop 0
	v_pk_mul_f32 v[48:49], v[48:49], v[52:53]
	s_nop 0
	v_cvt_pk_bf16_f32 v48, v48, v49
	v_mul_f32_e32 v49, 0xbfb8aa3b, v54
	v_exp_f32_e32 v49, v49
	s_nop 0
	v_add_f32_e32 v49, 1.0, v49
	v_rcp_f32_e32 v52, v49
	v_mul_f32_e32 v49, 0xbfb8aa3b, v55
	v_exp_f32_e32 v49, v49
	s_nop 0
	v_add_f32_e32 v49, 1.0, v49
	v_rcp_f32_e32 v53, v49
	s_nop 0
	v_pk_mul_f32 v[52:53], v[54:55], v[52:53]
	s_nop 0
	v_pk_mul_f32 v[50:51], v[50:51], v[52:53]
	s_nop 0
	v_cvt_pk_bf16_f32 v49, v50, v51
	v_mul_f32_e32 v50, 0xbfb8aa3b, v44
	v_mul_f32_e32 v51, 0xbfb8aa3b, v45
	v_exp_f32_e32 v50, v50
	v_exp_f32_e32 v51, v51
	global_store_dwordx2 v[64:65], v[48:49], off offset:32
	v_or_b32_e32 v48, 0x50, v122
	v_add_f32_e32 v50, 1.0, v50
	v_add_f32_e32 v51, 1.0, v51
	v_rcp_f32_e32 v50, v50
	v_rcp_f32_e32 v51, v51
	v_mad_i64_i32 v[48:49], s[2:3], v48, s46, v[120:121]
	v_pk_mul_f32 v[44:45], v[44:45], v[50:51]
	s_nop 0
	v_pk_mul_f32 v[40:41], v[40:41], v[44:45]
	s_nop 0
	v_cvt_pk_bf16_f32 v40, v40, v41
	v_mul_f32_e32 v41, 0xbfb8aa3b, v46
	v_exp_f32_e32 v41, v41
	s_nop 0
	v_add_f32_e32 v41, 1.0, v41
	v_rcp_f32_e32 v44, v41
	v_mul_f32_e32 v41, 0xbfb8aa3b, v47
	v_exp_f32_e32 v41, v41
	s_nop 0
	v_add_f32_e32 v41, 1.0, v41
	v_rcp_f32_e32 v45, v41
	s_nop 0
	v_pk_mul_f32 v[44:45], v[46:47], v[44:45]
	s_nop 0
	v_pk_mul_f32 v[42:43], v[42:43], v[44:45]
	s_nop 0
	v_cvt_pk_bf16_f32 v41, v42, v43
	global_store_dwordx2 v[48:49], v[40:41], off
	v_mul_f32_e32 v40, 0xbfb8aa3b, v36
	v_mul_f32_e32 v41, 0xbfb8aa3b, v37
	v_exp_f32_e32 v40, v40
	v_exp_f32_e32 v41, v41
	v_add_f32_e32 v40, 1.0, v40
	v_add_f32_e32 v41, 1.0, v41
	v_rcp_f32_e32 v40, v40
	v_rcp_f32_e32 v41, v41
	s_nop 0
	v_pk_mul_f32 v[36:37], v[36:37], v[40:41]
	s_nop 0
	v_pk_mul_f32 v[32:33], v[32:33], v[36:37]
	s_nop 0
	v_cvt_pk_bf16_f32 v32, v32, v33
	v_mul_f32_e32 v33, 0xbfb8aa3b, v38
	v_exp_f32_e32 v33, v33
	s_nop 0
	v_add_f32_e32 v33, 1.0, v33
	v_rcp_f32_e32 v36, v33
	v_mul_f32_e32 v33, 0xbfb8aa3b, v39
	v_exp_f32_e32 v33, v33
	s_nop 0
	v_add_f32_e32 v33, 1.0, v33
	v_rcp_f32_e32 v37, v33
	s_nop 0
	v_pk_mul_f32 v[36:37], v[38:39], v[36:37]
	s_nop 0
	v_pk_mul_f32 v[34:35], v[34:35], v[36:37]
	s_nop 0
	v_cvt_pk_bf16_f32 v33, v34, v35
	v_mul_f32_e32 v34, 0xbfb8aa3b, v28
	v_mul_f32_e32 v35, 0xbfb8aa3b, v29
	v_exp_f32_e32 v34, v34
	v_exp_f32_e32 v35, v35
	global_store_dwordx2 v[48:49], v[32:33], off offset:32
	v_or_b32_e32 v32, 0x60, v122
	v_add_f32_e32 v34, 1.0, v34
	v_add_f32_e32 v35, 1.0, v35
	v_rcp_f32_e32 v34, v34
	v_rcp_f32_e32 v35, v35
	v_mad_i64_i32 v[32:33], s[2:3], v32, s46, v[120:121]
	v_pk_mul_f32 v[28:29], v[28:29], v[34:35]
	s_nop 0
	v_pk_mul_f32 v[24:25], v[24:25], v[28:29]
	s_nop 0
	v_cvt_pk_bf16_f32 v24, v24, v25
	v_mul_f32_e32 v25, 0xbfb8aa3b, v30
	v_exp_f32_e32 v25, v25
	s_nop 0
	v_add_f32_e32 v25, 1.0, v25
	v_rcp_f32_e32 v28, v25
	v_mul_f32_e32 v25, 0xbfb8aa3b, v31
	v_exp_f32_e32 v25, v25
	s_nop 0
	v_add_f32_e32 v25, 1.0, v25
	v_rcp_f32_e32 v29, v25
	s_nop 0
	v_pk_mul_f32 v[28:29], v[30:31], v[28:29]
	s_nop 0
	v_pk_mul_f32 v[26:27], v[26:27], v[28:29]
	s_nop 0
	v_cvt_pk_bf16_f32 v25, v26, v27
	global_store_dwordx2 v[32:33], v[24:25], off
	v_mul_f32_e32 v24, 0xbfb8aa3b, v20
	v_mul_f32_e32 v25, 0xbfb8aa3b, v21
	v_exp_f32_e32 v24, v24
	v_exp_f32_e32 v25, v25
	v_add_f32_e32 v24, 1.0, v24
	v_add_f32_e32 v25, 1.0, v25
	v_rcp_f32_e32 v24, v24
	v_rcp_f32_e32 v25, v25
	s_nop 0
	v_pk_mul_f32 v[20:21], v[20:21], v[24:25]
	s_nop 0
	v_pk_mul_f32 v[16:17], v[16:17], v[20:21]
	s_nop 0
	v_cvt_pk_bf16_f32 v16, v16, v17
	v_mul_f32_e32 v17, 0xbfb8aa3b, v22
	v_exp_f32_e32 v17, v17
	s_nop 0
	v_add_f32_e32 v17, 1.0, v17
	v_rcp_f32_e32 v20, v17
	v_mul_f32_e32 v17, 0xbfb8aa3b, v23
	v_exp_f32_e32 v17, v17
	s_nop 0
	v_add_f32_e32 v17, 1.0, v17
	v_rcp_f32_e32 v21, v17
	s_nop 0
	v_pk_mul_f32 v[20:21], v[22:23], v[20:21]
	s_nop 0
	v_pk_mul_f32 v[18:19], v[18:19], v[20:21]
	s_nop 0
	v_cvt_pk_bf16_f32 v17, v18, v19
	v_mul_f32_e32 v18, 0xbfb8aa3b, v12
	v_mul_f32_e32 v19, 0xbfb8aa3b, v13
	v_exp_f32_e32 v18, v18
	v_exp_f32_e32 v19, v19
	global_store_dwordx2 v[32:33], v[16:17], off offset:32
	v_or_b32_e32 v16, 0x70, v122
	v_add_f32_e32 v18, 1.0, v18
	v_add_f32_e32 v19, 1.0, v19
	v_rcp_f32_e32 v18, v18
	v_rcp_f32_e32 v19, v19
	v_mad_i64_i32 v[16:17], s[2:3], v16, s46, v[120:121]
	v_readlane_b32 s2, v254, 22
	v_pk_mul_f32 v[12:13], v[12:13], v[18:19]
	s_add_i32 s10, s10, s2
	v_pk_mul_f32 v[8:9], v[8:9], v[12:13]
	s_cmpk_gt_u32 s12, 0x15f
	v_cvt_pk_bf16_f32 v8, v8, v9
	v_mul_f32_e32 v9, 0xbfb8aa3b, v14
	v_exp_f32_e32 v9, v9
	s_nop 0
	v_add_f32_e32 v9, 1.0, v9
	v_rcp_f32_e32 v12, v9
	v_mul_f32_e32 v9, 0xbfb8aa3b, v15
	v_exp_f32_e32 v9, v9
	s_nop 0
	v_add_f32_e32 v9, 1.0, v9
	v_rcp_f32_e32 v13, v9
	s_nop 0
	v_pk_mul_f32 v[12:13], v[14:15], v[12:13]
	s_nop 0
	v_pk_mul_f32 v[10:11], v[10:11], v[12:13]
	s_nop 0
	v_cvt_pk_bf16_f32 v9, v10, v11
	global_store_dwordx2 v[16:17], v[8:9], off
	v_mul_f32_e32 v8, 0xbfb8aa3b, v4
	v_mul_f32_e32 v9, 0xbfb8aa3b, v5
	v_exp_f32_e32 v8, v8
	v_exp_f32_e32 v9, v9
	v_add_f32_e32 v8, 1.0, v8
	v_add_f32_e32 v9, 1.0, v9
	v_rcp_f32_e32 v8, v8
	v_rcp_f32_e32 v9, v9
	s_nop 0
	v_pk_mul_f32 v[4:5], v[4:5], v[8:9]
	s_nop 0
	v_pk_mul_f32 v[0:1], v[0:1], v[4:5]
	s_nop 0
	v_cvt_pk_bf16_f32 v0, v0, v1
	v_mul_f32_e32 v1, 0xbfb8aa3b, v6
	v_exp_f32_e32 v1, v1
	s_nop 0
	v_add_f32_e32 v1, 1.0, v1
	v_rcp_f32_e32 v4, v1
	v_mul_f32_e32 v1, 0xbfb8aa3b, v7
	v_exp_f32_e32 v1, v1
	s_nop 0
	v_add_f32_e32 v1, 1.0, v1
	v_rcp_f32_e32 v5, v1
	s_nop 0
	v_pk_mul_f32 v[4:5], v[6:7], v[4:5]
	s_nop 0
	v_pk_mul_f32 v[2:3], v[2:3], v[4:5]
	s_nop 0
	v_cvt_pk_bf16_f32 v1, v2, v3
	global_store_dwordx2 v[16:17], v[0:1], off offset:32
	s_cbranch_scc0 .LBB0_850

.Lxb_local_6:
	s_mov_b64 s[14:15], exec
	v_mbcnt_lo_u32_b32 v0, s14, 0
	v_mbcnt_hi_u32_b32 v0, s15, v0
	v_cmp_eq_u32_e32 vcc, 0, v0
	s_waitcnt vmcnt(0)
	v_readlane_b32 s2, v255, 12
	s_cmp_lg_u32 s2, 0
	s_cbranch_scc1 .Lxb_noinv_6_0
	buffer_inv sc1
.Lxb_noinv_6_0:
	s_and_saveexec_b64 s[16:17], vcc
	s_cbranch_execz .LBB0_904
	s_bcnt1_i32_b64 s2, s[14:15]
	v_mov_b32_e32 v0, s2
	global_atomic_add v236, v0, s[10:11] offset:1024

.LBB0_909:
	s_and_b32 s2, s14, 7
	s_or_b32 s2, s2, s33
	s_lshl_b32 s15, s2, 8
	v_add_u32_e32 v0, s15, v227
	s_lshl_b32 s2, s14, 4
	v_add_u32_e32 v1, 32, v0
	s_and_b32 s16, s2, 0x380
	v_mad_i64_i32 v[204:205], s[2:3], v1, s10, 0
	v_add_u32_e32 v1, 64, v0
	v_mad_i64_i32 v[206:207], s[2:3], v1, s10, 0
	v_add_u32_e32 v1, 0x60, v0
	v_mad_i64_i32 v[208:209], s[2:3], v1, s10, 0
	v_add_u32_e32 v1, 0x80, v0
	v_mad_i64_i32 v[210:211], s[2:3], v1, s10, 0
	v_add_u32_e32 v1, 0xa0, v0
	v_mad_i64_i32 v[202:203], s[2:3], v0, s10, 0
	v_mad_i64_i32 v[212:213], s[2:3], v1, s10, 0
	v_add_u32_e32 v1, 0xc0, v0
	v_add_u32_e32 v0, 0xe0, v0
	v_mad_i64_i32 v[216:217], s[2:3], v0, s10, 0
	v_add_u32_e32 v0, s16, v227
	v_mad_i64_i32 v[214:215], s[2:3], v1, s10, 0
	v_add_u32_e32 v1, 32, v0
	v_mad_i64_i32 v[218:219], s[2:3], v0, s10, 0
	v_mad_i64_i32 v[220:221], s[2:3], v1, s10, 0
	v_add_u32_e32 v1, 64, v0
	v_add_u32_e32 v0, 0x60, v0
	v_mad_i64_i32 v[222:223], s[2:3], v1, s10, 0
	v_mad_i64_i32 v[224:225], s[2:3], v0, s10, 0
	v_lshl_add_u64 v[0:1], v[224:225], 1, v[194:195]
	v_lshl_add_u64 v[4:5], v[222:223], 1, v[194:195]
	v_lshl_add_u64 v[8:9], v[220:221], 1, v[194:195]
	v_lshl_add_u64 v[12:13], v[218:219], 1, v[194:195]
	v_lshl_add_u64 v[16:17], v[216:217], 1, v[192:193]
	v_lshl_add_u64 v[20:21], v[214:215], 1, v[192:193]
	v_lshl_add_u64 v[24:25], v[212:213], 1, v[192:193]
	v_lshl_add_u64 v[28:29], v[210:211], 1, v[192:193]
	v_lshl_add_u64 v[32:33], v[208:209], 1, v[192:193]
	v_lshl_add_u64 v[36:37], v[206:207], 1, v[192:193]
	v_lshl_add_u64 v[40:41], v[204:205], 1, v[192:193]
	v_lshl_add_u64 v[44:45], v[202:203], 1, v[192:193]
	global_load_dwordx4 v[0:3], v[0:1], off sc1
	s_nop 0
	global_load_dwordx4 v[4:7], v[4:5], off sc1
	s_nop 0
	global_load_dwordx4 v[8:11], v[8:9], off sc1
	s_nop 0
	global_load_dwordx4 v[12:15], v[12:13], off sc1
	s_nop 0
	global_load_dwordx4 v[16:19], v[16:17], off sc1
	s_nop 0
	global_load_dwordx4 v[20:23], v[20:21], off sc1
	s_nop 0
	global_load_dwordx4 v[24:27], v[24:25], off sc1
	s_nop 0
	global_load_dwordx4 v[28:31], v[28:29], off sc1
	s_nop 0
	global_load_dwordx4 v[32:35], v[32:33], off sc1
	s_nop 0
	global_load_dwordx4 v[36:39], v[36:37], off sc1
	s_nop 0
	global_load_dwordx4 v[40:43], v[40:41], off sc1
	s_nop 0
	global_load_dwordx4 v[44:47], v[44:45], off sc1
	v_mov_b32_e32 v144, 0
	s_mov_b32 s50, 64
	s_mov_b32 s2, s13
	v_mov_b32_e32 v145, v144
	v_mov_b32_e32 v146, v144
	v_mov_b32_e32 v147, v144
	v_mov_b32_e32 v148, v144
	v_mov_b32_e32 v149, v144
	v_mov_b32_e32 v150, v144
	v_mov_b32_e32 v151, v144
	v_mov_b32_e32 v152, v144
	v_mov_b32_e32 v153, v144
	v_mov_b32_e32 v154, v144
	v_mov_b32_e32 v155, v144
	v_mov_b32_e32 v156, v144
	v_mov_b32_e32 v157, v144
	v_mov_b32_e32 v158, v144
	v_mov_b32_e32 v159, v144
	v_mov_b32_e32 v116, v144
	v_mov_b32_e32 v117, v144
	v_mov_b32_e32 v118, v144
	v_mov_b32_e32 v119, v144
	v_mov_b32_e32 v128, v144
	v_mov_b32_e32 v129, v144
	v_mov_b32_e32 v130, v144
	v_mov_b32_e32 v131, v144
	v_mov_b32_e32 v136, v144
	v_mov_b32_e32 v137, v144
	v_mov_b32_e32 v138, v144
	v_mov_b32_e32 v139, v144
	v_mov_b32_e32 v140, v144
	v_mov_b32_e32 v141, v144
	v_mov_b32_e32 v142, v144
	v_mov_b32_e32 v143, v144
	v_mov_b32_e32 v100, v144
	v_mov_b32_e32 v101, v144
	v_mov_b32_e32 v102, v144
	v_mov_b32_e32 v103, v144
	v_mov_b32_e32 v112, v144
	v_mov_b32_e32 v113, v144
	v_mov_b32_e32 v114, v144
	v_mov_b32_e32 v115, v144
	v_mov_b32_e32 v124, v144
	v_mov_b32_e32 v125, v144
	v_mov_b32_e32 v126, v144
	v_mov_b32_e32 v127, v144
	v_mov_b32_e32 v132, v144
	v_mov_b32_e32 v133, v144
	v_mov_b32_e32 v134, v144
	v_mov_b32_e32 v135, v144
	v_mov_b32_e32 v88, v144
	v_mov_b32_e32 v89, v144
	v_mov_b32_e32 v90, v144
	v_mov_b32_e32 v91, v144
	v_mov_b32_e32 v96, v144
	v_mov_b32_e32 v97, v144
	v_mov_b32_e32 v98, v144
	v_mov_b32_e32 v99, v144
	v_mov_b32_e32 v108, v144
	v_mov_b32_e32 v109, v144
	v_mov_b32_e32 v110, v144
	v_mov_b32_e32 v111, v144
	v_mov_b32_e32 v120, v144
	v_mov_b32_e32 v121, v144
	v_mov_b32_e32 v122, v144
	v_mov_b32_e32 v123, v144
	v_mov_b32_e32 v80, v144
	v_mov_b32_e32 v81, v144
	v_mov_b32_e32 v82, v144
	v_mov_b32_e32 v83, v144
	v_mov_b32_e32 v84, v144
	v_mov_b32_e32 v85, v144
	v_mov_b32_e32 v86, v144
	v_mov_b32_e32 v87, v144
	v_mov_b32_e32 v92, v144
	v_mov_b32_e32 v93, v144
	v_mov_b32_e32 v94, v144
	v_mov_b32_e32 v95, v144
	v_mov_b32_e32 v104, v144
	v_mov_b32_e32 v105, v144
	v_mov_b32_e32 v106, v144
	v_mov_b32_e32 v107, v144
	v_mov_b32_e32 v48, v144
	v_mov_b32_e32 v49, v144
	v_mov_b32_e32 v50, v144
	v_mov_b32_e32 v51, v144
	v_mov_b32_e32 v52, v144
	v_mov_b32_e32 v53, v144
	v_mov_b32_e32 v54, v144
	v_mov_b32_e32 v55, v144
	v_mov_b32_e32 v56, v144
	v_mov_b32_e32 v57, v144
	v_mov_b32_e32 v58, v144
	v_mov_b32_e32 v59, v144
	v_mov_b32_e32 v72, v144
	v_mov_b32_e32 v73, v144
	v_mov_b32_e32 v74, v144
	v_mov_b32_e32 v75, v144
	v_mov_b32_e32 v76, v144
	v_mov_b32_e32 v77, v144
	v_mov_b32_e32 v78, v144
	v_mov_b32_e32 v79, v144
	v_mov_b32_e32 v68, v144
	v_mov_b32_e32 v69, v144
	v_mov_b32_e32 v70, v144
	v_mov_b32_e32 v71, v144
	v_mov_b32_e32 v64, v144
	v_mov_b32_e32 v65, v144
	v_mov_b32_e32 v66, v144
	v_mov_b32_e32 v67, v144
	v_mov_b32_e32 v60, v144
	v_mov_b32_e32 v61, v144
	v_mov_b32_e32 v62, v144
	v_mov_b32_e32 v63, v144
	v_mov_b32_e32 v160, v144
	v_mov_b32_e32 v161, v144
	v_mov_b32_e32 v162, v144
	v_mov_b32_e32 v163, v144
	v_mov_b32_e32 v164, v144
	v_mov_b32_e32 v165, v144
	v_mov_b32_e32 v166, v144
	v_mov_b32_e32 v167, v144
	v_mov_b32_e32 v168, v144
	v_mov_b32_e32 v169, v144
	v_mov_b32_e32 v170, v144
	v_mov_b32_e32 v171, v144
	v_mov_b32_e32 v172, v144
	v_mov_b32_e32 v173, v144
	v_mov_b32_e32 v174, v144
	v_mov_b32_e32 v175, v144
.LBB0_910:
	s_lshl_b64 s[8:9], s[50:51], 1
	s_waitcnt vmcnt(63) expcnt(7) lgkmcnt(15)
	s_barrier
	s_waitcnt vmcnt(0)
	ds_write_b128 v240, v[44:47]
	ds_write_b128 v240, v[40:43] offset:5120
	ds_write_b128 v240, v[36:39] offset:10240
	ds_write_b128 v240, v[32:35] offset:15360
	ds_write_b128 v240, v[28:31] offset:20480
	ds_write_b128 v240, v[24:27] offset:25600
	ds_write_b128 v240, v[20:23] offset:30720
	ds_write_b128 v240, v[16:19] offset:35840
	ds_write_b128 v240, v[12:15] offset:40960
	ds_write_b128 v240, v[8:11] offset:46080
	ds_write_b128 v240, v[4:7] offset:51200
	ds_write_b128 v240, v[0:3] offset:56320
	v_lshl_add_u64 v[0:1], v[192:193], 0, s[8:9]
	v_lshl_add_u64 v[2:3], v[194:195], 0, s[8:9]
	v_lshl_add_u64 v[4:5], v[202:203], 1, v[0:1]
	v_lshl_add_u64 v[6:7], v[204:205], 1, v[0:1]
	v_lshl_add_u64 v[8:9], v[206:207], 1, v[0:1]
	v_lshl_add_u64 v[10:11], v[208:209], 1, v[0:1]
	v_lshl_add_u64 v[12:13], v[210:211], 1, v[0:1]
	v_lshl_add_u64 v[14:15], v[212:213], 1, v[0:1]
	v_lshl_add_u64 v[16:17], v[214:215], 1, v[0:1]
	v_lshl_add_u64 v[0:1], v[216:217], 1, v[0:1]
	v_lshl_add_u64 v[176:177], v[218:219], 1, v[2:3]
	v_lshl_add_u64 v[178:179], v[220:221], 1, v[2:3]
	v_lshl_add_u64 v[180:181], v[222:223], 1, v[2:3]
	v_lshl_add_u64 v[2:3], v[224:225], 1, v[2:3]
	s_waitcnt lgkmcnt(0)
	s_barrier
	global_load_dwordx4 v[44:47], v[4:5], off sc1
	global_load_dwordx4 v[40:43], v[6:7], off sc1
	global_load_dwordx4 v[36:39], v[8:9], off sc1
	global_load_dwordx4 v[32:35], v[10:11], off sc1
	global_load_dwordx4 v[28:31], v[12:13], off sc1
	global_load_dwordx4 v[24:27], v[14:15], off sc1
	global_load_dwordx4 v[20:23], v[16:17], off sc1
	s_nop 0
	global_load_dwordx4 v[16:19], v[0:1], off sc1
	global_load_dwordx4 v[12:15], v[176:177], off sc1
	global_load_dwordx4 v[8:11], v[178:179], off sc1
	global_load_dwordx4 v[4:7], v[180:181], off sc1
	s_nop 0
	global_load_dwordx4 v[0:3], v[2:3], off sc1
	ds_read_b128 v[176:179], v241 offset:40960
	ds_read_b128 v[184:187], v241 offset:43520
	ds_read_b128 v[188:191], v241 offset:46080
	ds_read_b128 v[230:233], v241 offset:48640
	ds_read_b128 v[180:183], v239
	ds_read_b128 v[244:247], v239 offset:2560
	s_add_i32 s2, s2, -1
	s_add_i32 s50, s50, 64
	s_waitcnt lgkmcnt(1)
	v_mfma_f32_16x16x32_bf16 v[60:63], v[176:179], v[180:183], v[60:63]
	v_mfma_f32_16x16x32_bf16 v[64:67], v[184:187], v[180:183], v[64:67]
	v_mfma_f32_16x16x32_bf16 v[68:71], v[188:191], v[180:183], v[68:71]
	v_mfma_f32_16x16x32_bf16 v[76:79], v[230:233], v[180:183], v[76:79]
	ds_read_b128 v[180:183], v239 offset:5120
	s_waitcnt lgkmcnt(1)
	v_mfma_f32_16x16x32_bf16 v[72:75], v[176:179], v[244:247], v[72:75]
	v_mfma_f32_16x16x32_bf16 v[56:59], v[184:187], v[244:247], v[56:59]
	v_mfma_f32_16x16x32_bf16 v[52:55], v[188:191], v[244:247], v[52:55]
	v_mfma_f32_16x16x32_bf16 v[48:51], v[230:233], v[244:247], v[48:51]
	ds_read_b128 v[244:247], v239 offset:7680
	s_waitcnt lgkmcnt(1)
	v_mfma_f32_16x16x32_bf16 v[104:107], v[176:179], v[180:183], v[104:107]
	v_mfma_f32_16x16x32_bf16 v[92:95], v[184:187], v[180:183], v[92:95]
	v_mfma_f32_16x16x32_bf16 v[84:87], v[188:191], v[180:183], v[84:87]
	v_mfma_f32_16x16x32_bf16 v[80:83], v[230:233], v[180:183], v[80:83]
	ds_read_b128 v[180:183], v239 offset:10240
	s_waitcnt lgkmcnt(1)
	v_mfma_f32_16x16x32_bf16 v[120:123], v[176:179], v[244:247], v[120:123]
	v_mfma_f32_16x16x32_bf16 v[108:111], v[184:187], v[244:247], v[108:111]
	v_mfma_f32_16x16x32_bf16 v[96:99], v[188:191], v[244:247], v[96:99]
	v_mfma_f32_16x16x32_bf16 v[88:91], v[230:233], v[244:247], v[88:91]
	ds_read_b128 v[244:247], v239 offset:12800
	s_waitcnt lgkmcnt(1)
	v_mfma_f32_16x16x32_bf16 v[132:135], v[176:179], v[180:183], v[132:135]
	v_mfma_f32_16x16x32_bf16 v[124:127], v[184:187], v[180:183], v[124:127]
	v_mfma_f32_16x16x32_bf16 v[112:115], v[188:191], v[180:183], v[112:115]
	v_mfma_f32_16x16x32_bf16 v[100:103], v[230:233], v[180:183], v[100:103]
	ds_read_b128 v[180:183], v239 offset:15360
	s_waitcnt lgkmcnt(1)
	v_mfma_f32_16x16x32_bf16 v[140:143], v[176:179], v[244:247], v[140:143]
	v_mfma_f32_16x16x32_bf16 v[136:139], v[184:187], v[244:247], v[136:139]
	v_mfma_f32_16x16x32_bf16 v[128:131], v[188:191], v[244:247], v[128:131]
	v_mfma_f32_16x16x32_bf16 v[116:119], v[230:233], v[244:247], v[116:119]
	ds_read_b128 v[244:247], v242
	s_waitcnt lgkmcnt(1)
	v_mfma_f32_16x16x32_bf16 v[156:159], v[176:179], v[180:183], v[156:159]
	v_mfma_f32_16x16x32_bf16 v[152:155], v[184:187], v[180:183], v[152:155]
	v_mfma_f32_16x16x32_bf16 v[148:151], v[188:191], v[180:183], v[148:151]
	v_mfma_f32_16x16x32_bf16 v[144:147], v[230:233], v[180:183], v[144:147]
	ds_read_b128 v[180:183], v239 offset:64
	s_waitcnt lgkmcnt(1)
	v_mfma_f32_16x16x32_bf16 v[160:163], v[176:179], v[244:247], v[160:163]
	ds_read_b128 v[176:179], v241 offset:41024
	v_mfma_f32_16x16x32_bf16 v[164:167], v[184:187], v[244:247], v[164:167]
	ds_read_b128 v[184:187], v241 offset:43584
	v_mfma_f32_16x16x32_bf16 v[168:171], v[188:191], v[244:247], v[168:171]
	ds_read_b128 v[188:191], v241 offset:46144
	v_mfma_f32_16x16x32_bf16 v[172:175], v[230:233], v[244:247], v[172:175]
	ds_read_b128 v[230:233], v241 offset:48704
	ds_read_b128 v[244:247], v239 offset:2624
	s_waitcnt lgkmcnt(1)
	v_mfma_f32_16x16x32_bf16 v[60:63], v[176:179], v[180:183], v[60:63]
	v_mfma_f32_16x16x32_bf16 v[64:67], v[184:187], v[180:183], v[64:67]
	v_mfma_f32_16x16x32_bf16 v[68:71], v[188:191], v[180:183], v[68:71]
	v_mfma_f32_16x16x32_bf16 v[76:79], v[230:233], v[180:183], v[76:79]
	ds_read_b128 v[180:183], v239 offset:5184
	s_waitcnt lgkmcnt(1)
	v_mfma_f32_16x16x32_bf16 v[72:75], v[176:179], v[244:247], v[72:75]
	v_mfma_f32_16x16x32_bf16 v[56:59], v[184:187], v[244:247], v[56:59]
	v_mfma_f32_16x16x32_bf16 v[52:55], v[188:191], v[244:247], v[52:55]
	v_mfma_f32_16x16x32_bf16 v[48:51], v[230:233], v[244:247], v[48:51]
	ds_read_b128 v[244:247], v239 offset:7744
	s_waitcnt lgkmcnt(1)
	v_mfma_f32_16x16x32_bf16 v[104:107], v[176:179], v[180:183], v[104:107]
	v_mfma_f32_16x16x32_bf16 v[92:95], v[184:187], v[180:183], v[92:95]
	v_mfma_f32_16x16x32_bf16 v[84:87], v[188:191], v[180:183], v[84:87]
	v_mfma_f32_16x16x32_bf16 v[80:83], v[230:233], v[180:183], v[80:83]
	ds_read_b128 v[180:183], v239 offset:10304
	s_waitcnt lgkmcnt(1)
	v_mfma_f32_16x16x32_bf16 v[120:123], v[176:179], v[244:247], v[120:123]
	v_mfma_f32_16x16x32_bf16 v[108:111], v[184:187], v[244:247], v[108:111]
	v_mfma_f32_16x16x32_bf16 v[96:99], v[188:191], v[244:247], v[96:99]
	v_mfma_f32_16x16x32_bf16 v[88:91], v[230:233], v[244:247], v[88:91]
	ds_read_b128 v[244:247], v239 offset:12864
	s_waitcnt lgkmcnt(1)
	v_mfma_f32_16x16x32_bf16 v[132:135], v[176:179], v[180:183], v[132:135]
	v_mfma_f32_16x16x32_bf16 v[124:127], v[184:187], v[180:183], v[124:127]
	v_mfma_f32_16x16x32_bf16 v[112:115], v[188:191], v[180:183], v[112:115]
	v_mfma_f32_16x16x32_bf16 v[100:103], v[230:233], v[180:183], v[100:103]
	ds_read_b128 v[180:183], v239 offset:15424
	s_waitcnt lgkmcnt(1)
	v_mfma_f32_16x16x32_bf16 v[140:143], v[176:179], v[244:247], v[140:143]
	v_mfma_f32_16x16x32_bf16 v[136:139], v[184:187], v[244:247], v[136:139]
	v_mfma_f32_16x16x32_bf16 v[128:131], v[188:191], v[244:247], v[128:131]
	v_mfma_f32_16x16x32_bf16 v[116:119], v[230:233], v[244:247], v[116:119]
	ds_read_b128 v[244:247], v242 offset:64
	s_waitcnt lgkmcnt(1)
	v_mfma_f32_16x16x32_bf16 v[156:159], v[176:179], v[180:183], v[156:159]
	v_mfma_f32_16x16x32_bf16 v[152:155], v[184:187], v[180:183], v[152:155]
	v_mfma_f32_16x16x32_bf16 v[148:151], v[188:191], v[180:183], v[148:151]
	v_mfma_f32_16x16x32_bf16 v[144:147], v[230:233], v[180:183], v[144:147]
	s_waitcnt lgkmcnt(0)
	v_mfma_f32_16x16x32_bf16 v[160:163], v[176:179], v[244:247], v[160:163]
	v_mfma_f32_16x16x32_bf16 v[164:167], v[184:187], v[244:247], v[164:167]
	v_mfma_f32_16x16x32_bf16 v[168:171], v[188:191], v[244:247], v[168:171]
	v_mfma_f32_16x16x32_bf16 v[172:175], v[230:233], v[244:247], v[172:175]
	s_cmp_eq_u32 s2, 0
	s_cbranch_scc0 .LBB0_910
	s_add_i32 s2, s15, 0xffffe000
	s_ashr_i32 s2, s2, 12
	s_mulk_i32 s2, 0x1800
	s_add_i32 s8, s2, 0x1800
	s_and_b64 s[2:3], s[18:19], exec
	s_cselect_b32 s8, 0, s8
	s_ashr_i32 s9, s8, 31
	s_barrier
	s_waitcnt vmcnt(11)
	ds_write_b128 v240, v[44:47]
	s_waitcnt vmcnt(10)
	ds_write_b128 v240, v[40:43] offset:5120
	s_waitcnt vmcnt(9)
	ds_write_b128 v240, v[36:39] offset:10240
	s_waitcnt vmcnt(8)
	ds_write_b128 v240, v[32:35] offset:15360
	s_waitcnt vmcnt(7)
	ds_write_b128 v240, v[28:31] offset:20480
	s_waitcnt vmcnt(6)
	ds_write_b128 v240, v[24:27] offset:25600
	s_waitcnt vmcnt(5)
	ds_write_b128 v240, v[20:23] offset:30720
	s_waitcnt vmcnt(4)
	ds_write_b128 v240, v[16:19] offset:35840
	s_waitcnt vmcnt(3)
	ds_write_b128 v240, v[12:15] offset:40960
	s_waitcnt vmcnt(2)
	ds_write_b128 v240, v[8:11] offset:46080
	s_waitcnt vmcnt(1)
	ds_write_b128 v240, v[4:7] offset:51200
	s_waitcnt vmcnt(0)
	ds_write_b128 v240, v[0:3] offset:56320
	s_waitcnt lgkmcnt(0)
	s_barrier
	ds_read_b128 v[0:3], v241 offset:40960
	ds_read_b128 v[4:7], v241 offset:43520
	ds_read_b128 v[8:11], v241 offset:46080
	ds_read_b128 v[12:15], v241 offset:48640
	ds_read_b128 v[16:19], v239 offset:2560
	ds_read_b128 v[20:23], v239 offset:5120
	ds_read_b128 v[24:27], v239
	ds_read_b128 v[40:43], v239 offset:7680
	s_lshl_b64 s[2:3], s[8:9], 2
	s_waitcnt lgkmcnt(3)
	v_mfma_f32_16x16x32_bf16 v[44:47], v[0:3], v[16:19], v[72:75]
	s_add_u32 s2, s11, s2
	s_addc_u32 s3, s12, s3
	v_mov_b32_e32 v201, v197
	s_waitcnt lgkmcnt(1)
	v_mfma_f32_16x16x32_bf16 v[28:31], v[0:3], v[24:27], v[60:63]
	ds_read_b128 v[72:75], v239 offset:12800
	s_add_i32 s14, s14, s53
	s_cmp_gt_u32 s14, 63
	v_mfma_f32_16x16x32_bf16 v[32:35], v[4:7], v[24:27], v[64:67]
	v_mfma_f32_16x16x32_bf16 v[36:39], v[8:11], v[24:27], v[68:71]
	v_mfma_f32_16x16x32_bf16 v[24:27], v[12:15], v[24:27], v[76:79]
	v_mfma_f32_16x16x32_bf16 v[56:59], v[4:7], v[16:19], v[56:59]
	v_mfma_f32_16x16x32_bf16 v[52:55], v[8:11], v[16:19], v[52:55]
	v_mfma_f32_16x16x32_bf16 v[16:19], v[12:15], v[16:19], v[48:51]
	s_nop 2
	ds_read_b128 v[48:51], v239 offset:10240
	v_mfma_f32_16x16x32_bf16 v[60:63], v[0:3], v[20:23], v[104:107]
	v_mfma_f32_16x16x32_bf16 v[64:67], v[4:7], v[20:23], v[92:95]
	v_mfma_f32_16x16x32_bf16 v[68:71], v[8:11], v[20:23], v[84:87]
	s_nop 1
	ds_read_b128 v[92:95], v242
	v_mfma_f32_16x16x32_bf16 v[20:23], v[12:15], v[20:23], v[80:83]
	s_waitcnt lgkmcnt(3)
	v_mfma_f32_16x16x32_bf16 v[76:79], v[0:3], v[40:43], v[120:123]
	v_mfma_f32_16x16x32_bf16 v[80:83], v[4:7], v[40:43], v[108:111]
	v_mfma_f32_16x16x32_bf16 v[84:87], v[8:11], v[40:43], v[96:99]
	v_mfma_f32_16x16x32_bf16 v[40:43], v[12:15], v[40:43], v[88:91]
	s_nop 2
	ds_read_b128 v[88:91], v239 offset:15360
	s_waitcnt lgkmcnt(2)
	v_mfma_f32_16x16x32_bf16 v[176:179], v[0:3], v[48:51], v[132:135]
	v_mfma_f32_16x16x32_bf16 v[180:183], v[4:7], v[48:51], v[124:127]
	v_mfma_f32_16x16x32_bf16 v[184:187], v[8:11], v[48:51], v[112:115]
	v_mfma_f32_16x16x32_bf16 v[48:51], v[12:15], v[48:51], v[100:103]
	v_mfma_f32_16x16x32_bf16 v[188:191], v[0:3], v[72:75], v[140:143]
	v_mfma_f32_16x16x32_bf16 v[202:205], v[4:7], v[72:75], v[136:139]
	v_mfma_f32_16x16x32_bf16 v[206:209], v[8:11], v[72:75], v[128:131]
	v_mfma_f32_16x16x32_bf16 v[210:213], v[12:15], v[72:75], v[116:119]
	s_waitcnt lgkmcnt(0)
	v_mfma_f32_16x16x32_bf16 v[156:159], v[0:3], v[88:91], v[156:159]
	v_mfma_f32_16x16x32_bf16 v[152:155], v[4:7], v[88:91], v[152:155]
	v_mfma_f32_16x16x32_bf16 v[148:151], v[8:11], v[88:91], v[148:151]
	v_mfma_f32_16x16x32_bf16 v[144:147], v[12:15], v[88:91], v[144:147]
	v_mfma_f32_16x16x32_bf16 v[0:3], v[0:3], v[92:95], v[160:163]
	v_mfma_f32_16x16x32_bf16 v[4:7], v[4:7], v[92:95], v[164:167]
	v_mfma_f32_16x16x32_bf16 v[8:11], v[8:11], v[92:95], v[168:171]
	v_mfma_f32_16x16x32_bf16 v[160:163], v[12:15], v[92:95], v[172:175]
	ds_read_b128 v[12:15], v241 offset:41024
	ds_read_b128 v[164:167], v241 offset:43584
	ds_read_b128 v[168:171], v241 offset:46144
	ds_read_b128 v[172:175], v241 offset:48704
	ds_read_b128 v[72:75], v239 offset:2624
	ds_read_b128 v[88:91], v239 offset:5184
	ds_read_b128 v[92:95], v239 offset:64
	s_waitcnt lgkmcnt(0)
	v_mfma_f32_16x16x32_bf16 v[128:131], v[172:175], v[92:95], v[24:27]
	s_nop 2
	ds_read_b128 v[24:27], v239 offset:7744
	v_mfma_f32_16x16x32_bf16 v[116:119], v[168:171], v[72:75], v[52:55]
	v_mfma_f32_16x16x32_bf16 v[112:115], v[172:175], v[72:75], v[16:19]
	s_nop 1
	ds_read_b128 v[52:55], v239 offset:15424
	ds_read_b128 v[16:19], v239 offset:10304
	v_mfma_f32_16x16x32_bf16 v[108:111], v[12:15], v[88:91], v[60:63]
	v_mfma_f32_16x16x32_bf16 v[96:99], v[172:175], v[88:91], v[20:23]
	s_nop 1
	ds_read_b128 v[60:63], v242 offset:64
	ds_read_b128 v[20:23], v239 offset:12864
	v_mfma_f32_16x16x32_bf16 v[140:143], v[12:15], v[92:95], v[28:31]
	v_mfma_f32_16x16x32_bf16 v[136:139], v[164:167], v[92:95], v[32:35]
	v_mfma_f32_16x16x32_bf16 v[132:135], v[168:171], v[92:95], v[36:39]
	v_mfma_f32_16x16x32_bf16 v[124:127], v[12:15], v[72:75], v[44:47]
	v_mfma_f32_16x16x32_bf16 v[120:123], v[164:167], v[72:75], v[56:59]
	v_mfma_f32_16x16x32_bf16 v[104:107], v[164:167], v[88:91], v[64:67]
	v_mfma_f32_16x16x32_bf16 v[100:103], v[168:171], v[88:91], v[68:71]
	s_waitcnt lgkmcnt(4)
	v_mfma_f32_16x16x32_bf16 v[92:95], v[12:15], v[24:27], v[76:79]
	v_mfma_f32_16x16x32_bf16 v[88:91], v[164:167], v[24:27], v[80:83]
	v_mfma_f32_16x16x32_bf16 v[80:83], v[172:175], v[24:27], v[40:43]
	s_waitcnt lgkmcnt(2)
	v_mfma_f32_16x16x32_bf16 v[76:79], v[12:15], v[16:19], v[176:179]
	v_mfma_f32_16x16x32_bf16 v[72:75], v[164:167], v[16:19], v[180:183]
	v_mfma_f32_16x16x32_bf16 v[64:67], v[168:171], v[16:19], v[184:187]
	v_mfma_f32_16x16x32_bf16 v[56:59], v[172:175], v[16:19], v[48:51]
	s_waitcnt lgkmcnt(0)
	v_mfma_f32_16x16x32_bf16 v[48:51], v[12:15], v[20:23], v[188:191]
	v_mfma_f32_16x16x32_bf16 v[44:47], v[164:167], v[20:23], v[202:205]
	v_mfma_f32_16x16x32_bf16 v[40:43], v[168:171], v[20:23], v[206:209]
	v_mfma_f32_16x16x32_bf16 v[36:39], v[172:175], v[20:23], v[210:213]
	v_mfma_f32_16x16x32_bf16 v[32:35], v[12:15], v[52:55], v[156:159]
	v_mfma_f32_16x16x32_bf16 v[20:23], v[172:175], v[52:55], v[144:147]
	v_mfma_f32_16x16x32_bf16 v[16:19], v[12:15], v[60:63], v[0:3]
	s_nop 1
	v_add_u32_e32 v146, s15, v238
	v_ashrrev_i32_e32 v147, 31, v146
	v_mfma_f32_16x16x32_bf16 v[12:15], v[164:167], v[60:63], v[4:7]
	s_nop 2
	v_or_b32_e32 v4, s16, v226
	v_lshlrev_b32_e32 v196, 2, v4
	v_mfma_f32_16x16x32_bf16 v[84:87], v[168:171], v[24:27], v[84:87]
	v_lshl_add_u64 v[4:5], s[2:3], 0, v[196:197]
	v_lshl_add_u64 v[144:145], v[198:199], 0, v[196:197]
	v_lshl_add_u64 v[4:5], v[4:5], 0, v[200:201]
	v_mfma_f32_16x16x32_bf16 v[24:27], v[168:171], v[52:55], v[148:151]
	s_nop 2
	v_lshlrev_b64 v[148:149], 12, v[146:147]
	v_mfma_f32_16x16x32_bf16 v[28:31], v[164:167], v[52:55], v[152:155]
	s_nop 2
	v_lshl_add_u64 v[152:153], v[144:145], 0, v[148:149]
	v_mfma_f32_16x16x32_bf16 v[8:11], v[168:171], v[60:63], v[8:11]
	v_mfma_f32_16x16x32_bf16 v[0:3], v[172:175], v[60:63], v[160:163]
	global_load_dwordx4 v[68:71], v[4:5], off sc1
	global_load_dwordx4 v[60:63], v[4:5], off offset:64 sc1
	global_load_dwordx4 v[52:55], v[4:5], off offset:128 sc1
	s_nop 0
	global_load_dwordx4 v[4:7], v[4:5], off offset:192 sc1
	s_nop 0
	global_load_dwordx4 v[148:151], v[152:153], off sc1
	s_waitcnt vmcnt(0)
	v_pk_fma_f32 v[142:143], v[142:143], v[70:71], v[150:151]
	v_pk_fma_f32 v[140:141], v[140:141], v[68:69], v[148:149]
	global_store_dwordx4 v[152:153], v[140:143], off
	global_load_dwordx4 v[140:143], v[152:153], off offset:64 sc1
	s_waitcnt vmcnt(0)
	v_pk_fma_f32 v[138:139], v[138:139], v[62:63], v[142:143]
	v_pk_fma_f32 v[136:137], v[136:137], v[60:61], v[140:141]
	global_store_dwordx4 v[152:153], v[136:139], off offset:64
	global_load_dwordx4 v[136:139], v[152:153], off offset:128 sc1
	s_waitcnt vmcnt(0)
	v_pk_fma_f32 v[134:135], v[134:135], v[54:55], v[138:139]
	v_pk_fma_f32 v[132:133], v[132:133], v[52:53], v[136:137]
	global_store_dwordx4 v[152:153], v[132:135], off offset:128
	global_load_dwordx4 v[132:135], v[152:153], off offset:192 sc1
	s_waitcnt vmcnt(0)
	v_pk_fma_f32 v[130:131], v[130:131], v[6:7], v[134:135]
	v_pk_fma_f32 v[128:129], v[128:129], v[4:5], v[132:133]
	global_store_dwordx4 v[152:153], v[128:131], off offset:192
	s_nop 1
	v_or_b32_e32 v128, 16, v146
	v_ashrrev_i32_e32 v129, 31, v128
	v_lshlrev_b64 v[128:129], 12, v[128:129]
	v_lshl_add_u64 v[132:133], v[144:145], 0, v[128:129]
	global_load_dwordx4 v[128:131], v[132:133], off sc1
	s_waitcnt vmcnt(0)
	v_pk_fma_f32 v[126:127], v[126:127], v[70:71], v[130:131]
	v_pk_fma_f32 v[124:125], v[124:125], v[68:69], v[128:129]
	global_store_dwordx4 v[132:133], v[124:127], off
	global_load_dwordx4 v[124:127], v[132:133], off offset:64 sc1
	s_waitcnt vmcnt(0)
	v_pk_fma_f32 v[122:123], v[122:123], v[62:63], v[126:127]
	v_pk_fma_f32 v[120:121], v[120:121], v[60:61], v[124:125]
	global_store_dwordx4 v[132:133], v[120:123], off offset:64
	global_load_dwordx4 v[120:123], v[132:133], off offset:128 sc1
	s_waitcnt vmcnt(0)
	v_pk_fma_f32 v[118:119], v[118:119], v[54:55], v[122:123]
	v_pk_fma_f32 v[116:117], v[116:117], v[52:53], v[120:121]
	global_store_dwordx4 v[132:133], v[116:119], off offset:128
	global_load_dwordx4 v[116:119], v[132:133], off offset:192 sc1
	s_waitcnt vmcnt(0)
	v_pk_fma_f32 v[114:115], v[114:115], v[6:7], v[118:119]
	v_pk_fma_f32 v[112:113], v[112:113], v[4:5], v[116:117]
	global_store_dwordx4 v[132:133], v[112:115], off offset:192
	s_nop 1
	v_or_b32_e32 v112, 32, v146
	v_ashrrev_i32_e32 v113, 31, v112
	v_lshlrev_b64 v[112:113], 12, v[112:113]
	v_lshl_add_u64 v[116:117], v[144:145], 0, v[112:113]
	global_load_dwordx4 v[112:115], v[116:117], off sc1
	s_waitcnt vmcnt(0)
	v_pk_fma_f32 v[110:111], v[110:111], v[70:71], v[114:115]
	v_pk_fma_f32 v[108:109], v[108:109], v[68:69], v[112:113]
	global_store_dwordx4 v[116:117], v[108:111], off
	global_load_dwordx4 v[108:111], v[116:117], off offset:64 sc1
	s_waitcnt vmcnt(0)
	v_pk_fma_f32 v[106:107], v[106:107], v[62:63], v[110:111]
	v_pk_fma_f32 v[104:105], v[104:105], v[60:61], v[108:109]
	global_store_dwordx4 v[116:117], v[104:107], off offset:64
	global_load_dwordx4 v[104:107], v[116:117], off offset:128 sc1
	s_waitcnt vmcnt(0)
	v_pk_fma_f32 v[102:103], v[102:103], v[54:55], v[106:107]
	v_pk_fma_f32 v[100:101], v[100:101], v[52:53], v[104:105]
	global_store_dwordx4 v[116:117], v[100:103], off offset:128
	global_load_dwordx4 v[100:103], v[116:117], off offset:192 sc1
	s_waitcnt vmcnt(0)
	v_pk_fma_f32 v[98:99], v[98:99], v[6:7], v[102:103]
	v_pk_fma_f32 v[96:97], v[96:97], v[4:5], v[100:101]
	global_store_dwordx4 v[116:117], v[96:99], off offset:192
	s_nop 1
	v_or_b32_e32 v96, 48, v146
	v_ashrrev_i32_e32 v97, 31, v96
	v_lshlrev_b64 v[96:97], 12, v[96:97]
	v_lshl_add_u64 v[100:101], v[144:145], 0, v[96:97]
	global_load_dwordx4 v[96:99], v[100:101], off sc1
	s_waitcnt vmcnt(0)
	v_pk_fma_f32 v[94:95], v[94:95], v[70:71], v[98:99]
	v_pk_fma_f32 v[92:93], v[92:93], v[68:69], v[96:97]
	global_store_dwordx4 v[100:101], v[92:95], off
	global_load_dwordx4 v[92:95], v[100:101], off offset:64 sc1
	s_waitcnt vmcnt(0)
	v_pk_fma_f32 v[90:91], v[90:91], v[62:63], v[94:95]
	v_pk_fma_f32 v[88:89], v[88:89], v[60:61], v[92:93]
	global_store_dwordx4 v[100:101], v[88:91], off offset:64
	global_load_dwordx4 v[88:91], v[100:101], off offset:128 sc1
	s_waitcnt vmcnt(0)
	v_pk_fma_f32 v[86:87], v[86:87], v[54:55], v[90:91]
	v_pk_fma_f32 v[84:85], v[84:85], v[52:53], v[88:89]
	global_store_dwordx4 v[100:101], v[84:87], off offset:128
	global_load_dwordx4 v[84:87], v[100:101], off offset:192 sc1
	s_waitcnt vmcnt(0)
	v_pk_fma_f32 v[82:83], v[82:83], v[6:7], v[86:87]
	v_pk_fma_f32 v[80:81], v[80:81], v[4:5], v[84:85]
	global_store_dwordx4 v[100:101], v[80:83], off offset:192
	s_nop 1
	v_or_b32_e32 v80, 64, v146
	v_ashrrev_i32_e32 v81, 31, v80
	v_lshlrev_b64 v[80:81], 12, v[80:81]
	v_lshl_add_u64 v[84:85], v[144:145], 0, v[80:81]
	global_load_dwordx4 v[80:83], v[84:85], off sc1
	s_waitcnt vmcnt(0)
	v_pk_fma_f32 v[78:79], v[78:79], v[70:71], v[82:83]
	v_pk_fma_f32 v[76:77], v[76:77], v[68:69], v[80:81]
	global_store_dwordx4 v[84:85], v[76:79], off
	global_load_dwordx4 v[76:79], v[84:85], off offset:64 sc1
	s_waitcnt vmcnt(0)
	v_pk_fma_f32 v[74:75], v[74:75], v[62:63], v[78:79]
	v_pk_fma_f32 v[72:73], v[72:73], v[60:61], v[76:77]
	global_store_dwordx4 v[84:85], v[72:75], off offset:64
	global_load_dwordx4 v[72:75], v[84:85], off offset:128 sc1
	s_waitcnt vmcnt(0)
	v_pk_fma_f32 v[66:67], v[66:67], v[54:55], v[74:75]
	v_pk_fma_f32 v[64:65], v[64:65], v[52:53], v[72:73]
	global_store_dwordx4 v[84:85], v[64:67], off offset:128
	global_load_dwordx4 v[64:67], v[84:85], off offset:192 sc1
	s_waitcnt vmcnt(0)
	v_pk_fma_f32 v[58:59], v[58:59], v[6:7], v[66:67]
	v_pk_fma_f32 v[56:57], v[56:57], v[4:5], v[64:65]
	global_store_dwordx4 v[84:85], v[56:59], off offset:192
	s_nop 1
	v_or_b32_e32 v56, 0x50, v146
	v_ashrrev_i32_e32 v57, 31, v56
	v_lshlrev_b64 v[56:57], 12, v[56:57]
	v_lshl_add_u64 v[64:65], v[144:145], 0, v[56:57]
	global_load_dwordx4 v[56:59], v[64:65], off sc1
	s_waitcnt vmcnt(0)
	v_pk_fma_f32 v[50:51], v[50:51], v[70:71], v[58:59]
	v_pk_fma_f32 v[48:49], v[48:49], v[68:69], v[56:57]
	global_store_dwordx4 v[64:65], v[48:51], off
	global_load_dwordx4 v[48:51], v[64:65], off offset:64 sc1
	s_waitcnt vmcnt(0)
	v_pk_fma_f32 v[46:47], v[46:47], v[62:63], v[50:51]
	v_pk_fma_f32 v[44:45], v[44:45], v[60:61], v[48:49]
	global_store_dwordx4 v[64:65], v[44:47], off offset:64
	global_load_dwordx4 v[44:47], v[64:65], off offset:128 sc1
	s_waitcnt vmcnt(0)
	v_pk_fma_f32 v[42:43], v[42:43], v[54:55], v[46:47]
	v_pk_fma_f32 v[40:41], v[40:41], v[52:53], v[44:45]
	global_store_dwordx4 v[64:65], v[40:43], off offset:128
	global_load_dwordx4 v[40:43], v[64:65], off offset:192 sc1
	s_waitcnt vmcnt(0)
	v_pk_fma_f32 v[38:39], v[38:39], v[6:7], v[42:43]
	v_pk_fma_f32 v[36:37], v[36:37], v[4:5], v[40:41]
	global_store_dwordx4 v[64:65], v[36:39], off offset:192
	s_nop 1
	v_or_b32_e32 v36, 0x60, v146
	v_ashrrev_i32_e32 v37, 31, v36
	v_lshlrev_b64 v[36:37], 12, v[36:37]
	v_lshl_add_u64 v[40:41], v[144:145], 0, v[36:37]
	global_load_dwordx4 v[36:39], v[40:41], off sc1
	s_waitcnt vmcnt(0)
	v_pk_fma_f32 v[34:35], v[34:35], v[70:71], v[38:39]
	v_pk_fma_f32 v[32:33], v[32:33], v[68:69], v[36:37]
	global_store_dwordx4 v[40:41], v[32:35], off
	global_load_dwordx4 v[32:35], v[40:41], off offset:64 sc1
	s_waitcnt vmcnt(0)
	v_pk_fma_f32 v[30:31], v[30:31], v[62:63], v[34:35]
	v_pk_fma_f32 v[28:29], v[28:29], v[60:61], v[32:33]
	global_store_dwordx4 v[40:41], v[28:31], off offset:64
	global_load_dwordx4 v[28:31], v[40:41], off offset:128 sc1
	s_waitcnt vmcnt(0)
	v_pk_fma_f32 v[26:27], v[26:27], v[54:55], v[30:31]
	v_pk_fma_f32 v[24:25], v[24:25], v[52:53], v[28:29]
	global_store_dwordx4 v[40:41], v[24:27], off offset:128
	global_load_dwordx4 v[24:27], v[40:41], off offset:192 sc1
	s_waitcnt vmcnt(0)
	v_pk_fma_f32 v[22:23], v[22:23], v[6:7], v[26:27]
	v_pk_fma_f32 v[20:21], v[20:21], v[4:5], v[24:25]
	global_store_dwordx4 v[40:41], v[20:23], off offset:192
	s_nop 1
	v_or_b32_e32 v20, 0x70, v146
	v_ashrrev_i32_e32 v21, 31, v20
	v_lshlrev_b64 v[20:21], 12, v[20:21]
	v_lshl_add_u64 v[20:21], v[144:145], 0, v[20:21]
	global_load_dwordx4 v[22:25], v[20:21], off sc1
	s_waitcnt vmcnt(0)
	v_pk_fma_f32 v[18:19], v[18:19], v[70:71], v[24:25]
	v_pk_fma_f32 v[16:17], v[16:17], v[68:69], v[22:23]
	global_store_dwordx4 v[20:21], v[16:19], off
	global_load_dwordx4 v[16:19], v[20:21], off offset:64 sc1
	s_waitcnt vmcnt(0)
	v_pk_fma_f32 v[14:15], v[14:15], v[62:63], v[18:19]
	v_pk_fma_f32 v[12:13], v[12:13], v[60:61], v[16:17]
	global_store_dwordx4 v[20:21], v[12:15], off offset:64
	global_load_dwordx4 v[12:15], v[20:21], off offset:128 sc1
	s_waitcnt vmcnt(0)
	v_pk_fma_f32 v[10:11], v[10:11], v[54:55], v[14:15]
	v_pk_fma_f32 v[8:9], v[8:9], v[52:53], v[12:13]
	global_store_dwordx4 v[20:21], v[8:11], off offset:128
	global_load_dwordx4 v[8:11], v[20:21], off offset:192 sc1
	s_waitcnt vmcnt(0)
	v_pk_fma_f32 v[2:3], v[2:3], v[6:7], v[10:11]
	v_pk_fma_f32 v[0:1], v[0:1], v[4:5], v[8:9]
	global_store_dwordx4 v[20:21], v[0:3], off offset:192
	s_cbranch_scc0 .LBB0_909

.Lxb_noinv_7_0:
	s_and_saveexec_b64 s[14:15], vcc
	s_cbranch_execz .LBB0_791
	s_bcnt1_i32_b64 s2, s[12:13]
	v_mov_b32_e32 v0, s2
	global_atomic_add v236, v0, s[10:11] offset:1024
	s_branch .LBB0_791

.LBB0_965:
	v_mov_b32_e32 v0, v228
	s_add_i32 s0, s0, s7
	v_ashrrev_i32_e32 v3, 6, v0
	v_add_u32_e32 v4, s1, v3
	v_ashrrev_i32_e32 v5, 31, v4
	v_lshlrev_b32_e32 v0, 4, v0
	v_lshlrev_b64 v[4:5], 12, v[4:5]
	v_and_b32_e32 v0, 0x3f0, v0
	v_lshl_add_u64 v[4:5], s[88:89], 0, v[4:5]
	v_lshl_add_u64 v[24:25], v[4:5], 0, v[0:1]
	global_load_dwordx4 v[4:7], v[24:25], off sc1
	global_load_dwordx4 v[8:11], v[24:25], off offset:1024 sc1
	global_load_dwordx4 v[12:15], v[24:25], off offset:2048 sc1
	global_load_dwordx4 v[16:19], v[24:25], off offset:3072 sc1
	global_load_dwordx4 v[20:23], v0, s[10:11] sc1
	s_add_i32 s1, s1, s35
	s_cmpk_gt_i32 s0, 0x1ff
	s_waitcnt vmcnt(4)
	v_mov_b32_e32 v28, v5
	s_waitcnt vmcnt(3)
	v_mov_b32_e32 v29, v9
	v_mov_b32_e32 v26, v4
	v_mov_b32_e32 v27, v8
	s_waitcnt vmcnt(2)
	v_mov_b32_e32 v36, v13
	s_waitcnt vmcnt(1)
	v_mov_b32_e32 v37, v17
	v_pk_mul_f32 v[28:29], v[28:29], v[28:29]
	v_mov_b32_e32 v30, v6
	v_mov_b32_e32 v31, v10
	v_mov_b32_e32 v34, v12
	v_mov_b32_e32 v35, v16
	v_pk_mul_f32 v[36:37], v[36:37], v[36:37]
	v_pk_fma_f32 v[26:27], v[26:27], v[26:27], v[28:29]
	v_mov_b32_e32 v32, v7
	v_mov_b32_e32 v33, v11
	v_mov_b32_e32 v38, v14
	v_mov_b32_e32 v39, v18
	v_pk_fma_f32 v[28:29], v[34:35], v[34:35], v[36:37]
	v_pk_fma_f32 v[26:27], v[30:31], v[30:31], v[26:27]
	v_mov_b32_e32 v40, v15
	v_mov_b32_e32 v41, v19
	v_pk_fma_f32 v[28:29], v[38:39], v[38:39], v[28:29]
	v_pk_fma_f32 v[26:27], v[32:33], v[32:33], v[26:27]
	v_pk_fma_f32 v[28:29], v[40:41], v[40:41], v[28:29]
	v_add_f32_e32 v3, v26, v27
	v_add_f32_e32 v3, v3, v28
	v_add_f32_e32 v3, v3, v29
	s_nop 1
	v_add_f32_dpp v3, v3, v3 quad_perm:[1,0,3,2] row_mask:0xf bank_mask:0xf bound_ctrl:1
	s_nop 1
	v_add_f32_dpp v3, v3, v3 quad_perm:[2,3,0,1] row_mask:0xf bank_mask:0xf bound_ctrl:1
	s_nop 1
	v_add_f32_dpp v3, v3, v3 row_ror:4 row_mask:0xf bank_mask:0xf bound_ctrl:1
	s_nop 1
	v_add_f32_dpp v3, v3, v3 row_ror:8 row_mask:0xf bank_mask:0xf bound_ctrl:1
	s_nop 0
	v_readlane_b32 s3, v3, 16
	v_readlane_b32 s6, v3, 48
	v_readlane_b32 s4, v3, 0
	v_readlane_b32 s5, v3, 32
	v_mov_b32_e32 v26, s3
	v_mov_b32_e32 v27, s6
	v_pk_add_f32 v[26:27], s[4:5], v[26:27]
	s_nop 0
	v_add_f32_e32 v3, v26, v27
	v_fmamk_f32 v3, v3, 0x3a800000, v2
	v_mul_f32_e32 v26, 0x4b800000, v3
	v_cmp_gt_f32_e32 vcc, s2, v3
	s_nop 1
	v_cndmask_b32_e32 v3, v3, v26, vcc
	v_rsq_f32_e32 v3, v3
	s_nop 0
	v_mul_f32_e32 v26, 0x45800000, v3
	v_cndmask_b32_e32 v26, v3, v26, vcc
	v_pk_mul_f32 v[4:5], v[4:5], v[26:27] op_sel_hi:[1,0]
	v_pk_mul_f32 v[6:7], v[6:7], v[26:27] op_sel_hi:[1,0]
	s_waitcnt vmcnt(0)
	v_pk_mul_f32 v[4:5], v[20:21], v[4:5]
	v_pk_mul_f32 v[6:7], v[22:23], v[6:7]
	global_store_dwordx4 v[24:25], v[4:7], off
	global_load_dwordx4 v[4:7], v0, s[10:11] offset:1024 sc1
	v_pk_mul_f32 v[8:9], v[8:9], v[26:27] op_sel_hi:[1,0]
	v_pk_mul_f32 v[10:11], v[10:11], v[26:27] op_sel_hi:[1,0]
	s_waitcnt vmcnt(0)
	v_pk_mul_f32 v[4:5], v[4:5], v[8:9]
	v_pk_mul_f32 v[6:7], v[6:7], v[10:11]
	global_store_dwordx4 v[24:25], v[4:7], off offset:1024
	global_load_dwordx4 v[4:7], v0, s[10:11] offset:2048 sc1
	v_pk_mul_f32 v[8:9], v[12:13], v[26:27] op_sel_hi:[1,0]
	v_pk_mul_f32 v[10:11], v[14:15], v[26:27] op_sel_hi:[1,0]
	s_waitcnt vmcnt(0)
	v_pk_mul_f32 v[4:5], v[8:9], v[4:5]
	v_pk_mul_f32 v[6:7], v[10:11], v[6:7]
	global_store_dwordx4 v[24:25], v[4:7], off offset:2048
	global_load_dwordx4 v[4:7], v0, s[10:11] offset:3072 sc1
	v_pk_mul_f32 v[8:9], v[16:17], v[26:27] op_sel_hi:[1,0]
	v_pk_mul_f32 v[10:11], v[18:19], v[26:27] op_sel_hi:[1,0]
	s_waitcnt vmcnt(0)
	v_pk_mul_f32 v[4:5], v[8:9], v[4:5]
	v_pk_mul_f32 v[6:7], v[10:11], v[6:7]
	global_store_dwordx4 v[24:25], v[4:7], off offset:3072
	s_cbranch_scc0 .LBB0_965
